# v112 + write-through (sc1) stores in the residual epilogues of the four one-round GEMM phases, so the barrier's L2 write-back finds less dirty data
# speedup vs baseline: 1.0086x; 1.0086x over previous
.LBB0_850:
	ds_read_b128 v[140:143], v147
	ds_read_b128 v[150:153], v147 offset:1024
	ds_read_b128 v[154:157], v147 offset:2048
	ds_read_b128 v[158:161], v147 offset:3072
	s_add_u32 s76, s74, 0x100
	s_addc_u32 s77, s75, 0
	s_cmp_eq_u32 s73, 28
	s_cselect_b32 s5, s0, s77
	s_cselect_b32 s4, s1, s76
	s_cselect_b32 s51, s46, s67
	s_cselect_b32 s50, s47, s61
	s_add_i32 m0, s23, 0xc000
	ds_read_b128 v[162:165], v148
	ds_read_b128 v[166:169], v148 offset:1024
	ds_read_b128 v[170:173], v148 offset:2048
	ds_read_b128 v[174:177], v148 offset:3072
	ds_read_b128 v[178:181], v148 offset:4096
	ds_read_b128 v[182:185], v148 offset:5120
	ds_read_b128 v[186:189], v148 offset:6144
	ds_read_b128 v[190:193], v148 offset:7168
	global_load_lds_dwordx4 v132, s[74:75]
	s_add_i32 m0, s23, 0xe000
	s_nop 0
	global_load_lds_dwordx4 v134, s[74:75]
	s_waitcnt lgkmcnt(8)
	s_barrier
	s_waitcnt lgkmcnt(0)
	s_waitcnt lgkmcnt(0)
	v_mfma_f32_16x16x32_bf16 v[124:127], v[140:143], v[162:165], v[124:127]
	v_mfma_f32_16x16x32_bf16 v[100:103], v[154:157], v[162:165], v[100:103]
	v_mfma_f32_16x16x32_bf16 v[120:123], v[140:143], v[170:173], v[120:123]
	v_mfma_f32_16x16x32_bf16 v[96:99], v[154:157], v[170:173], v[96:99]
	v_mfma_f32_16x16x32_bf16 v[116:119], v[140:143], v[178:181], v[116:119]
	v_mfma_f32_16x16x32_bf16 v[88:91], v[154:157], v[178:181], v[88:91]
	v_mfma_f32_16x16x32_bf16 v[112:115], v[140:143], v[186:189], v[112:115]
	v_mfma_f32_16x16x32_bf16 v[80:83], v[154:157], v[186:189], v[80:83]
	v_mfma_f32_16x16x32_bf16 v[124:127], v[150:153], v[166:169], v[124:127]
	v_mfma_f32_16x16x32_bf16 v[100:103], v[158:161], v[166:169], v[100:103]
	v_mfma_f32_16x16x32_bf16 v[120:123], v[150:153], v[174:177], v[120:123]
	v_mfma_f32_16x16x32_bf16 v[96:99], v[158:161], v[174:177], v[96:99]
	v_mfma_f32_16x16x32_bf16 v[116:119], v[150:153], v[182:185], v[116:119]
	v_mfma_f32_16x16x32_bf16 v[88:91], v[158:161], v[182:185], v[88:91]
	v_mfma_f32_16x16x32_bf16 v[112:115], v[150:153], v[190:193], v[112:115]
	v_mfma_f32_16x16x32_bf16 v[80:83], v[158:161], v[190:193], v[80:83]
	s_barrier
	s_add_i32 s42, s37, s21
	s_add_u32 s98, s50, s16
	s_addc_u32 s99, s51, s17
	s_mov_b32 m0, s42
	ds_read_b128 v[194:197], v149
	ds_read_b128 v[198:201], v149 offset:1024
	ds_read_b128 v[202:205], v149 offset:2048
	ds_read_b128 v[206:209], v149 offset:3072
	global_load_lds_dwordx4 v130, s[50:51]
	s_add_i32 m0, s42, 0x2000
	s_nop 0
	global_load_lds_dwordx4 v128, s[50:51]
	s_barrier
	s_waitcnt lgkmcnt(0)
	s_waitcnt lgkmcnt(0)
	v_mfma_f32_16x16x32_bf16 v[68:71], v[194:197], v[162:165], v[68:71]
	v_mfma_f32_16x16x32_bf16 v[40:43], v[202:205], v[162:165], v[40:43]
	v_mfma_f32_16x16x32_bf16 v[60:63], v[194:197], v[170:173], v[60:63]
	v_mfma_f32_16x16x32_bf16 v[32:35], v[202:205], v[170:173], v[32:35]
	v_mfma_f32_16x16x32_bf16 v[52:55], v[194:197], v[178:181], v[52:55]
	v_mfma_f32_16x16x32_bf16 v[24:27], v[202:205], v[178:181], v[24:27]
	v_mfma_f32_16x16x32_bf16 v[48:51], v[194:197], v[186:189], v[48:51]
	v_mfma_f32_16x16x32_bf16 v[16:19], v[202:205], v[186:189], v[16:19]
	v_mfma_f32_16x16x32_bf16 v[68:71], v[198:201], v[166:169], v[68:71]
	v_mfma_f32_16x16x32_bf16 v[40:43], v[206:209], v[166:169], v[40:43]
	v_mfma_f32_16x16x32_bf16 v[60:63], v[198:201], v[174:177], v[60:63]
	v_mfma_f32_16x16x32_bf16 v[32:35], v[206:209], v[174:177], v[32:35]
	v_mfma_f32_16x16x32_bf16 v[52:55], v[198:201], v[182:185], v[52:55]
	v_mfma_f32_16x16x32_bf16 v[24:27], v[206:209], v[182:185], v[24:27]
	v_mfma_f32_16x16x32_bf16 v[48:51], v[198:201], v[190:193], v[48:51]
	v_mfma_f32_16x16x32_bf16 v[16:19], v[206:209], v[190:193], v[16:19]
	s_mov_b32 m0, s23
	s_add_u32 s100, s4, s16
	s_addc_u32 s101, s5, s17
	s_barrier
	ds_read_b128 v[162:165], v148 offset:16384
	ds_read_b128 v[166:169], v148 offset:17408
	ds_read_b128 v[170:173], v148 offset:18432
	ds_read_b128 v[174:177], v148 offset:19456
	ds_read_b128 v[178:181], v148 offset:20480
	ds_read_b128 v[182:185], v148 offset:21504
	ds_read_b128 v[186:189], v148 offset:22528
	ds_read_b128 v[190:193], v148 offset:23552
	global_load_lds_dwordx4 v130, s[4:5]
	s_mov_b32 m0, s24
	s_nop 0
	global_load_lds_dwordx4 v128, s[4:5]
	s_barrier
	s_waitcnt lgkmcnt(0)
	s_waitcnt lgkmcnt(0)
	v_mfma_f32_16x16x32_bf16 v[108:111], v[140:143], v[162:165], v[108:111]
	v_mfma_f32_16x16x32_bf16 v[76:79], v[154:157], v[162:165], v[76:79]
	v_mfma_f32_16x16x32_bf16 v[104:107], v[140:143], v[170:173], v[104:107]
	v_mfma_f32_16x16x32_bf16 v[72:75], v[154:157], v[170:173], v[72:75]
	v_mfma_f32_16x16x32_bf16 v[92:95], v[140:143], v[178:181], v[92:95]
	v_mfma_f32_16x16x32_bf16 v[64:67], v[154:157], v[178:181], v[64:67]
	v_mfma_f32_16x16x32_bf16 v[84:87], v[140:143], v[186:189], v[84:87]
	v_mfma_f32_16x16x32_bf16 v[56:59], v[154:157], v[186:189], v[56:59]
	v_mfma_f32_16x16x32_bf16 v[108:111], v[150:153], v[166:169], v[108:111]
	v_mfma_f32_16x16x32_bf16 v[76:79], v[158:161], v[166:169], v[76:79]
	v_mfma_f32_16x16x32_bf16 v[104:107], v[150:153], v[174:177], v[104:107]
	v_mfma_f32_16x16x32_bf16 v[72:75], v[158:161], v[174:177], v[72:75]
	v_mfma_f32_16x16x32_bf16 v[92:95], v[150:153], v[182:185], v[92:95]
	v_mfma_f32_16x16x32_bf16 v[64:67], v[158:161], v[182:185], v[64:67]
	v_mfma_f32_16x16x32_bf16 v[84:87], v[150:153], v[190:193], v[84:87]
	v_mfma_f32_16x16x32_bf16 v[56:59], v[158:161], v[190:193], v[56:59]
	s_barrier
	s_add_u32 s42, s50, 0x80000
	s_addc_u32 s43, s51, 0
	s_add_i32 s44, s40, s21
	s_mov_b32 m0, s44
	s_nop 0
	global_load_lds_dwordx4 v130, s[42:43]
	s_add_i32 m0, s44, 0x2000
	s_nop 0
	global_load_lds_dwordx4 v128, s[42:43]
	s_waitcnt vmcnt(6)
	s_barrier
	v_mfma_f32_16x16x32_bf16 v[44:47], v[194:197], v[162:165], v[44:47]
	v_mfma_f32_16x16x32_bf16 v[12:15], v[202:205], v[162:165], v[12:15]
	v_mfma_f32_16x16x32_bf16 v[36:39], v[194:197], v[170:173], v[36:39]
	v_mfma_f32_16x16x32_bf16 v[8:11], v[202:205], v[170:173], v[8:11]
	v_mfma_f32_16x16x32_bf16 v[28:31], v[194:197], v[178:181], v[28:31]
	v_mfma_f32_16x16x32_bf16 v[4:7], v[202:205], v[178:181], v[4:7]
	v_mfma_f32_16x16x32_bf16 v[20:23], v[194:197], v[186:189], v[20:23]
	v_mfma_f32_16x16x32_bf16 v[0:3], v[202:205], v[186:189], v[0:3]
	v_mfma_f32_16x16x32_bf16 v[44:47], v[198:201], v[166:169], v[44:47]
	v_mfma_f32_16x16x32_bf16 v[12:15], v[206:209], v[166:169], v[12:15]
	v_mfma_f32_16x16x32_bf16 v[36:39], v[198:201], v[174:177], v[36:39]
	v_mfma_f32_16x16x32_bf16 v[8:11], v[206:209], v[174:177], v[8:11]
	v_mfma_f32_16x16x32_bf16 v[28:31], v[198:201], v[182:185], v[28:31]
	v_mfma_f32_16x16x32_bf16 v[4:7], v[206:209], v[182:185], v[4:7]
	v_mfma_f32_16x16x32_bf16 v[20:23], v[198:201], v[190:193], v[20:23]
	v_mfma_f32_16x16x32_bf16 v[0:3], v[206:209], v[190:193], v[0:3]
	s_add_i32 s42, 0, 0x18000
	v_add_u32_e32 v158, s42, v145
	s_barrier
	ds_read_b128 v[140:143], v158
	ds_read_b128 v[150:153], v158 offset:1024
	ds_read_b128 v[154:157], v158 offset:2048
	ds_read_b128 v[158:161], v158 offset:3072
	s_add_u32 s4, s4, 0x80000
	s_addc_u32 s5, s5, 0
	s_mov_b32 m0, s25
	ds_read_b128 v[162:165], v148 offset:32768
	ds_read_b128 v[166:169], v148 offset:33792
	ds_read_b128 v[170:173], v148 offset:34816
	ds_read_b128 v[174:177], v148 offset:35840
	ds_read_b128 v[178:181], v148 offset:36864
	ds_read_b128 v[182:185], v148 offset:37888
	ds_read_b128 v[186:189], v148 offset:38912
	ds_read_b128 v[190:193], v148 offset:39936
	global_load_lds_dwordx4 v130, s[4:5]
	s_mov_b32 m0, s28
	s_nop 0
	global_load_lds_dwordx4 v128, s[4:5]
	s_waitcnt lgkmcnt(8)
	s_barrier
	s_waitcnt lgkmcnt(0)
	s_waitcnt lgkmcnt(0)
	v_mfma_f32_16x16x32_bf16 v[124:127], v[140:143], v[162:165], v[124:127]
	v_mfma_f32_16x16x32_bf16 v[100:103], v[154:157], v[162:165], v[100:103]
	v_mfma_f32_16x16x32_bf16 v[120:123], v[140:143], v[170:173], v[120:123]
	v_mfma_f32_16x16x32_bf16 v[96:99], v[154:157], v[170:173], v[96:99]
	v_mfma_f32_16x16x32_bf16 v[116:119], v[140:143], v[178:181], v[116:119]
	v_mfma_f32_16x16x32_bf16 v[88:91], v[154:157], v[178:181], v[88:91]
	v_mfma_f32_16x16x32_bf16 v[112:115], v[140:143], v[186:189], v[112:115]
	v_mfma_f32_16x16x32_bf16 v[80:83], v[154:157], v[186:189], v[80:83]
	v_mfma_f32_16x16x32_bf16 v[124:127], v[150:153], v[166:169], v[124:127]
	v_mfma_f32_16x16x32_bf16 v[100:103], v[158:161], v[166:169], v[100:103]
	v_mfma_f32_16x16x32_bf16 v[120:123], v[150:153], v[174:177], v[120:123]
	v_mfma_f32_16x16x32_bf16 v[96:99], v[158:161], v[174:177], v[96:99]
	v_mfma_f32_16x16x32_bf16 v[116:119], v[150:153], v[182:185], v[116:119]
	v_mfma_f32_16x16x32_bf16 v[88:91], v[158:161], v[182:185], v[88:91]
	v_mfma_f32_16x16x32_bf16 v[112:115], v[150:153], v[190:193], v[112:115]
	v_mfma_f32_16x16x32_bf16 v[80:83], v[158:161], v[190:193], v[80:83]
	s_barrier
	s_add_i32 s43, 0, 0x1c000
	s_add_i32 s4, s42, s21
	v_add_u32_e32 v206, s43, v145
	s_mov_b32 m0, s4
	ds_read_b128 v[194:197], v206
	ds_read_b128 v[198:201], v206 offset:1024
	ds_read_b128 v[202:205], v206 offset:2048
	ds_read_b128 v[206:209], v206 offset:3072
	global_load_lds_dwordx4 v130, s[98:99]
	s_add_i32 m0, s4, 0x2000
	s_nop 0
	global_load_lds_dwordx4 v128, s[98:99]
	s_barrier
	s_waitcnt lgkmcnt(0)
	s_waitcnt lgkmcnt(0)
	v_mfma_f32_16x16x32_bf16 v[68:71], v[194:197], v[162:165], v[68:71]
	v_mfma_f32_16x16x32_bf16 v[40:43], v[202:205], v[162:165], v[40:43]
	v_mfma_f32_16x16x32_bf16 v[60:63], v[194:197], v[170:173], v[60:63]
	v_mfma_f32_16x16x32_bf16 v[32:35], v[202:205], v[170:173], v[32:35]
	v_mfma_f32_16x16x32_bf16 v[52:55], v[194:197], v[178:181], v[52:55]
	v_mfma_f32_16x16x32_bf16 v[24:27], v[202:205], v[178:181], v[24:27]
	v_mfma_f32_16x16x32_bf16 v[48:51], v[194:197], v[186:189], v[48:51]
	v_mfma_f32_16x16x32_bf16 v[16:19], v[202:205], v[186:189], v[16:19]
	v_mfma_f32_16x16x32_bf16 v[68:71], v[198:201], v[166:169], v[68:71]
	v_mfma_f32_16x16x32_bf16 v[40:43], v[206:209], v[166:169], v[40:43]
	v_mfma_f32_16x16x32_bf16 v[60:63], v[198:201], v[174:177], v[60:63]
	v_mfma_f32_16x16x32_bf16 v[32:35], v[206:209], v[174:177], v[32:35]
	v_mfma_f32_16x16x32_bf16 v[52:55], v[198:201], v[182:185], v[52:55]
	v_mfma_f32_16x16x32_bf16 v[24:27], v[206:209], v[182:185], v[24:27]
	v_mfma_f32_16x16x32_bf16 v[48:51], v[198:201], v[190:193], v[48:51]
	v_mfma_f32_16x16x32_bf16 v[16:19], v[206:209], v[190:193], v[16:19]
	s_mov_b32 m0, s33
	s_barrier
	ds_read_b128 v[162:165], v148 offset:49152
	ds_read_b128 v[166:169], v148 offset:50176
	ds_read_b128 v[170:173], v148 offset:51200
	ds_read_b128 v[174:177], v148 offset:52224
	ds_read_b128 v[178:181], v148 offset:53248
	ds_read_b128 v[182:185], v148 offset:54272
	ds_read_b128 v[186:189], v148 offset:55296
	ds_read_b128 v[190:193], v148 offset:56320
	global_load_lds_dwordx4 v130, s[100:101]
	s_mov_b32 m0, s36
	s_nop 0
	global_load_lds_dwordx4 v128, s[100:101]
	s_barrier
	s_waitcnt lgkmcnt(0)
	s_waitcnt lgkmcnt(0)
	v_mfma_f32_16x16x32_bf16 v[108:111], v[140:143], v[162:165], v[108:111]
	v_mfma_f32_16x16x32_bf16 v[76:79], v[154:157], v[162:165], v[76:79]
	v_mfma_f32_16x16x32_bf16 v[104:107], v[140:143], v[170:173], v[104:107]
	v_mfma_f32_16x16x32_bf16 v[72:75], v[154:157], v[170:173], v[72:75]
	v_mfma_f32_16x16x32_bf16 v[92:95], v[140:143], v[178:181], v[92:95]
	v_mfma_f32_16x16x32_bf16 v[64:67], v[154:157], v[178:181], v[64:67]
	v_mfma_f32_16x16x32_bf16 v[84:87], v[140:143], v[186:189], v[84:87]
	v_mfma_f32_16x16x32_bf16 v[56:59], v[154:157], v[186:189], v[56:59]
	v_mfma_f32_16x16x32_bf16 v[108:111], v[150:153], v[166:169], v[108:111]
	v_mfma_f32_16x16x32_bf16 v[76:79], v[158:161], v[166:169], v[76:79]
	v_mfma_f32_16x16x32_bf16 v[104:107], v[150:153], v[174:177], v[104:107]
	v_mfma_f32_16x16x32_bf16 v[72:75], v[158:161], v[174:177], v[72:75]
	v_mfma_f32_16x16x32_bf16 v[92:95], v[150:153], v[182:185], v[92:95]
	v_mfma_f32_16x16x32_bf16 v[64:67], v[158:161], v[182:185], v[64:67]
	v_mfma_f32_16x16x32_bf16 v[84:87], v[150:153], v[190:193], v[84:87]
	v_mfma_f32_16x16x32_bf16 v[56:59], v[158:161], v[190:193], v[56:59]
	s_barrier
	s_add_u32 s4, s50, 0x80080
	s_addc_u32 s5, s51, 0
	s_add_i32 s42, s43, s21
	s_mov_b32 m0, s42
	s_nop 0
	global_load_lds_dwordx4 v130, s[4:5]
	s_add_i32 m0, s42, 0x2000
	s_nop 0
	global_load_lds_dwordx4 v128, s[4:5]
	s_waitcnt vmcnt(6)
	s_barrier
	v_mfma_f32_16x16x32_bf16 v[44:47], v[194:197], v[162:165], v[44:47]
	v_mfma_f32_16x16x32_bf16 v[12:15], v[202:205], v[162:165], v[12:15]
	v_mfma_f32_16x16x32_bf16 v[36:39], v[194:197], v[170:173], v[36:39]
	v_mfma_f32_16x16x32_bf16 v[8:11], v[202:205], v[170:173], v[8:11]
	v_mfma_f32_16x16x32_bf16 v[28:31], v[194:197], v[178:181], v[28:31]
	v_mfma_f32_16x16x32_bf16 v[4:7], v[202:205], v[178:181], v[4:7]
	v_mfma_f32_16x16x32_bf16 v[20:23], v[194:197], v[186:189], v[20:23]
	v_mfma_f32_16x16x32_bf16 v[0:3], v[202:205], v[186:189], v[0:3]
	v_mfma_f32_16x16x32_bf16 v[44:47], v[198:201], v[166:169], v[44:47]
	v_mfma_f32_16x16x32_bf16 v[12:15], v[206:209], v[166:169], v[12:15]
	v_mfma_f32_16x16x32_bf16 v[36:39], v[198:201], v[174:177], v[36:39]
	v_mfma_f32_16x16x32_bf16 v[8:11], v[206:209], v[174:177], v[8:11]
	v_mfma_f32_16x16x32_bf16 v[28:31], v[198:201], v[182:185], v[28:31]
	v_mfma_f32_16x16x32_bf16 v[4:7], v[206:209], v[182:185], v[4:7]
	v_mfma_f32_16x16x32_bf16 v[20:23], v[198:201], v[190:193], v[20:23]
	v_mfma_f32_16x16x32_bf16 v[0:3], v[206:209], v[190:193], v[0:3]
	s_add_i32 s73, s73, 2
	s_add_u32 s61, s61, 0x100
	s_addc_u32 s67, s67, 0
	s_cmp_gt_u32 s73, 29
	s_mov_b64 s[74:75], s[76:77]
	s_barrier
	s_cbranch_scc0 .LBB0_850
	v_lshl_or_b32 v140, s41, 8, v146
	v_lshl_add_u32 v143, s72, 8, v144
	v_lshlrev_b32_e32 v140, 2, v140
	v_lshl_add_u32 v143, v143, 13, v140
	s_mov_b32 s41, s60
	s_mov_b32 s72, s66
	s_mov_b64 s[50:51], s[70:71]
	s_mov_b64 s[74:75], s[68:69]
	v_mov_b32_e32 v141, v143
	v_mov_b32_e32 v142, v143
	global_load_dwordx4 v[166:169], v140, s[14:15] offset:0
	global_load_dwordx4 v[150:153], v141, s[10:11] offset:0
	v_add_u32_e32 v141, 0x20000, v141
	global_load_dwordx4 v[154:157], v141, s[10:11] offset:0
	v_add_u32_e32 v141, 0x20000, v141
	global_load_dwordx4 v[158:161], v141, s[10:11] offset:0
	v_add_u32_e32 v141, 0x20000, v141
	global_load_dwordx4 v[162:165], v141, s[10:11] offset:0
	v_add_u32_e32 v141, 0xa0000, v141
	s_waitcnt vmcnt(3)
	v_pk_fma_f32 v[150:151], v[124:125], v[166:167], v[150:151]
	v_pk_fma_f32 v[152:153], v[126:127], v[168:169], v[152:153]
	global_store_dwordx4 v142, v[150:153], s[12:13] offset:0 sc1
	v_add_u32_e32 v142, 0x20000, v142
	global_load_dwordx4 v[150:153], v141, s[10:11] offset:0
	v_add_u32_e32 v141, 0x20000, v141
	s_waitcnt vmcnt(4)
	v_pk_fma_f32 v[154:155], v[120:121], v[166:167], v[154:155]
	v_pk_fma_f32 v[156:157], v[122:123], v[168:169], v[156:157]
	global_store_dwordx4 v142, v[154:157], s[12:13] offset:0 sc1
	v_add_u32_e32 v142, 0x20000, v142
	global_load_dwordx4 v[154:157], v141, s[10:11] offset:0
	v_add_u32_e32 v141, 0x20000, v141
	s_waitcnt vmcnt(5)
	v_pk_fma_f32 v[158:159], v[116:117], v[166:167], v[158:159]
	v_pk_fma_f32 v[160:161], v[118:119], v[168:169], v[160:161]
	global_store_dwordx4 v142, v[158:161], s[12:13] offset:0 sc1
	v_add_u32_e32 v142, 0x20000, v142
	global_load_dwordx4 v[158:161], v141, s[10:11] offset:0
	v_add_u32_e32 v141, 0x20000, v141
	s_waitcnt vmcnt(6)
	v_pk_fma_f32 v[162:163], v[112:113], v[166:167], v[162:163]
	v_pk_fma_f32 v[164:165], v[114:115], v[168:169], v[164:165]
	global_store_dwordx4 v142, v[162:165], s[12:13] offset:0 sc1
	v_add_u32_e32 v142, 0xa0000, v142
	global_load_dwordx4 v[162:165], v141, s[10:11] offset:0
	v_add_u32_e32 v141, 0x20000, v141
	s_waitcnt vmcnt(6)
	v_pk_fma_f32 v[150:151], v[108:109], v[166:167], v[150:151]
	v_pk_fma_f32 v[152:153], v[110:111], v[168:169], v[152:153]
	global_store_dwordx4 v142, v[150:153], s[12:13] offset:0 sc1
	v_add_u32_e32 v142, 0x20000, v142
	s_waitcnt vmcnt(5)
	v_pk_fma_f32 v[154:155], v[104:105], v[166:167], v[154:155]
	v_pk_fma_f32 v[156:157], v[106:107], v[168:169], v[156:157]
	global_store_dwordx4 v142, v[154:157], s[12:13] offset:0 sc1
	v_add_u32_e32 v142, 0x20000, v142
	s_waitcnt vmcnt(4)
	v_pk_fma_f32 v[158:159], v[92:93], v[166:167], v[158:159]
	v_pk_fma_f32 v[160:161], v[94:95], v[168:169], v[160:161]
	global_store_dwordx4 v142, v[158:161], s[12:13] offset:0 sc1
	v_add_u32_e32 v142, 0x20000, v142
	s_waitcnt vmcnt(3)
	v_pk_fma_f32 v[162:163], v[84:85], v[166:167], v[162:163]
	v_pk_fma_f32 v[164:165], v[86:87], v[168:169], v[164:165]
	global_store_dwordx4 v142, v[162:165], s[12:13] offset:0 sc1
	v_add_u32_e32 v142, 0x20000, v142
	v_mov_b32_e32 v141, v143
	v_mov_b32_e32 v142, v143
	global_load_dwordx4 v[166:169], v140, s[14:15] offset:64
	global_load_dwordx4 v[150:153], v141, s[10:11] offset:64
	v_add_u32_e32 v141, 0x20000, v141
	global_load_dwordx4 v[154:157], v141, s[10:11] offset:64
	v_add_u32_e32 v141, 0x20000, v141
	global_load_dwordx4 v[158:161], v141, s[10:11] offset:64
	v_add_u32_e32 v141, 0x20000, v141
	global_load_dwordx4 v[162:165], v141, s[10:11] offset:64
	v_add_u32_e32 v141, 0xa0000, v141
	s_waitcnt vmcnt(3)
	v_pk_fma_f32 v[150:151], v[100:101], v[166:167], v[150:151]
	v_pk_fma_f32 v[152:153], v[102:103], v[168:169], v[152:153]
	global_store_dwordx4 v142, v[150:153], s[12:13] offset:64 sc1
	v_add_u32_e32 v142, 0x20000, v142
	global_load_dwordx4 v[150:153], v141, s[10:11] offset:64
	v_add_u32_e32 v141, 0x20000, v141
	s_waitcnt vmcnt(4)
	v_pk_fma_f32 v[154:155], v[96:97], v[166:167], v[154:155]
	v_pk_fma_f32 v[156:157], v[98:99], v[168:169], v[156:157]
	global_store_dwordx4 v142, v[154:157], s[12:13] offset:64 sc1
	v_add_u32_e32 v142, 0x20000, v142
	global_load_dwordx4 v[154:157], v141, s[10:11] offset:64
	v_add_u32_e32 v141, 0x20000, v141
	s_waitcnt vmcnt(5)
	v_pk_fma_f32 v[158:159], v[88:89], v[166:167], v[158:159]
	v_pk_fma_f32 v[160:161], v[90:91], v[168:169], v[160:161]
	global_store_dwordx4 v142, v[158:161], s[12:13] offset:64 sc1
	v_add_u32_e32 v142, 0x20000, v142
	global_load_dwordx4 v[158:161], v141, s[10:11] offset:64
	v_add_u32_e32 v141, 0x20000, v141
	s_waitcnt vmcnt(6)
	v_pk_fma_f32 v[162:163], v[80:81], v[166:167], v[162:163]
	v_pk_fma_f32 v[164:165], v[82:83], v[168:169], v[164:165]
	global_store_dwordx4 v142, v[162:165], s[12:13] offset:64 sc1
	v_add_u32_e32 v142, 0xa0000, v142
	global_load_dwordx4 v[162:165], v141, s[10:11] offset:64
	v_add_u32_e32 v141, 0x20000, v141
	s_waitcnt vmcnt(6)
	v_pk_fma_f32 v[150:151], v[76:77], v[166:167], v[150:151]
	v_pk_fma_f32 v[152:153], v[78:79], v[168:169], v[152:153]
	global_store_dwordx4 v142, v[150:153], s[12:13] offset:64 sc1
	v_add_u32_e32 v142, 0x20000, v142
	s_waitcnt vmcnt(5)
	v_pk_fma_f32 v[154:155], v[72:73], v[166:167], v[154:155]
	v_pk_fma_f32 v[156:157], v[74:75], v[168:169], v[156:157]
	global_store_dwordx4 v142, v[154:157], s[12:13] offset:64 sc1
	v_add_u32_e32 v142, 0x20000, v142
	s_waitcnt vmcnt(4)
	v_pk_fma_f32 v[158:159], v[64:65], v[166:167], v[158:159]
	v_pk_fma_f32 v[160:161], v[66:67], v[168:169], v[160:161]
	global_store_dwordx4 v142, v[158:161], s[12:13] offset:64 sc1
	v_add_u32_e32 v142, 0x20000, v142
	s_waitcnt vmcnt(3)
	v_pk_fma_f32 v[162:163], v[56:57], v[166:167], v[162:163]
	v_pk_fma_f32 v[164:165], v[58:59], v[168:169], v[164:165]
	global_store_dwordx4 v142, v[162:165], s[12:13] offset:64 sc1
	v_add_u32_e32 v142, 0x20000, v142
	v_mov_b32_e32 v141, v143
	v_mov_b32_e32 v142, v143
	global_load_dwordx4 v[166:169], v140, s[14:15] offset:512
	global_load_dwordx4 v[150:153], v141, s[10:11] offset:512
	v_add_u32_e32 v141, 0x20000, v141
	global_load_dwordx4 v[154:157], v141, s[10:11] offset:512
	v_add_u32_e32 v141, 0x20000, v141
	global_load_dwordx4 v[158:161], v141, s[10:11] offset:512
	v_add_u32_e32 v141, 0x20000, v141
	global_load_dwordx4 v[162:165], v141, s[10:11] offset:512
	v_add_u32_e32 v141, 0xa0000, v141
	s_waitcnt vmcnt(3)
	v_pk_fma_f32 v[150:151], v[68:69], v[166:167], v[150:151]
	v_pk_fma_f32 v[152:153], v[70:71], v[168:169], v[152:153]
	global_store_dwordx4 v142, v[150:153], s[12:13] offset:512 sc1
	v_add_u32_e32 v142, 0x20000, v142
	global_load_dwordx4 v[150:153], v141, s[10:11] offset:512
	v_add_u32_e32 v141, 0x20000, v141
	s_waitcnt vmcnt(4)
	v_pk_fma_f32 v[154:155], v[60:61], v[166:167], v[154:155]
	v_pk_fma_f32 v[156:157], v[62:63], v[168:169], v[156:157]
	global_store_dwordx4 v142, v[154:157], s[12:13] offset:512 sc1
	v_add_u32_e32 v142, 0x20000, v142
	global_load_dwordx4 v[154:157], v141, s[10:11] offset:512
	v_add_u32_e32 v141, 0x20000, v141
	s_waitcnt vmcnt(5)
	v_pk_fma_f32 v[158:159], v[52:53], v[166:167], v[158:159]
	v_pk_fma_f32 v[160:161], v[54:55], v[168:169], v[160:161]
	global_store_dwordx4 v142, v[158:161], s[12:13] offset:512 sc1
	v_add_u32_e32 v142, 0x20000, v142
	global_load_dwordx4 v[158:161], v141, s[10:11] offset:512
	v_add_u32_e32 v141, 0x20000, v141
	s_waitcnt vmcnt(6)
	v_pk_fma_f32 v[162:163], v[48:49], v[166:167], v[162:163]
	v_pk_fma_f32 v[164:165], v[50:51], v[168:169], v[164:165]
	global_store_dwordx4 v142, v[162:165], s[12:13] offset:512 sc1
	v_add_u32_e32 v142, 0xa0000, v142
	global_load_dwordx4 v[162:165], v141, s[10:11] offset:512
	v_add_u32_e32 v141, 0x20000, v141
	s_waitcnt vmcnt(6)
	v_pk_fma_f32 v[150:151], v[44:45], v[166:167], v[150:151]
	v_pk_fma_f32 v[152:153], v[46:47], v[168:169], v[152:153]
	global_store_dwordx4 v142, v[150:153], s[12:13] offset:512 sc1
	v_add_u32_e32 v142, 0x20000, v142
	s_waitcnt vmcnt(5)
	v_pk_fma_f32 v[154:155], v[36:37], v[166:167], v[154:155]
	v_pk_fma_f32 v[156:157], v[38:39], v[168:169], v[156:157]
	global_store_dwordx4 v142, v[154:157], s[12:13] offset:512 sc1
	v_add_u32_e32 v142, 0x20000, v142
	s_waitcnt vmcnt(4)
	v_pk_fma_f32 v[158:159], v[28:29], v[166:167], v[158:159]
	v_pk_fma_f32 v[160:161], v[30:31], v[168:169], v[160:161]
	global_store_dwordx4 v142, v[158:161], s[12:13] offset:512 sc1
	v_add_u32_e32 v142, 0x20000, v142
	s_waitcnt vmcnt(3)
	v_pk_fma_f32 v[162:163], v[20:21], v[166:167], v[162:163]
	v_pk_fma_f32 v[164:165], v[22:23], v[168:169], v[164:165]
	global_store_dwordx4 v142, v[162:165], s[12:13] offset:512 sc1
	v_add_u32_e32 v142, 0x20000, v142
	v_mov_b32_e32 v141, v143
	v_mov_b32_e32 v142, v143
	global_load_dwordx4 v[166:169], v140, s[14:15] offset:576
	global_load_dwordx4 v[150:153], v141, s[10:11] offset:576
	v_add_u32_e32 v141, 0x20000, v141
	global_load_dwordx4 v[154:157], v141, s[10:11] offset:576
	v_add_u32_e32 v141, 0x20000, v141
	global_load_dwordx4 v[158:161], v141, s[10:11] offset:576
	v_add_u32_e32 v141, 0x20000, v141
	global_load_dwordx4 v[162:165], v141, s[10:11] offset:576
	v_add_u32_e32 v141, 0xa0000, v141
	s_waitcnt vmcnt(3)
	v_pk_fma_f32 v[150:151], v[40:41], v[166:167], v[150:151]
	v_pk_fma_f32 v[152:153], v[42:43], v[168:169], v[152:153]
	global_store_dwordx4 v142, v[150:153], s[12:13] offset:576 sc1
	v_add_u32_e32 v142, 0x20000, v142
	global_load_dwordx4 v[150:153], v141, s[10:11] offset:576
	v_add_u32_e32 v141, 0x20000, v141
	s_waitcnt vmcnt(4)
	v_pk_fma_f32 v[154:155], v[32:33], v[166:167], v[154:155]
	v_pk_fma_f32 v[156:157], v[34:35], v[168:169], v[156:157]
	global_store_dwordx4 v142, v[154:157], s[12:13] offset:576 sc1
	v_add_u32_e32 v142, 0x20000, v142
	global_load_dwordx4 v[154:157], v141, s[10:11] offset:576
	v_add_u32_e32 v141, 0x20000, v141
	s_waitcnt vmcnt(5)
	v_pk_fma_f32 v[158:159], v[24:25], v[166:167], v[158:159]
	v_pk_fma_f32 v[160:161], v[26:27], v[168:169], v[160:161]
	global_store_dwordx4 v142, v[158:161], s[12:13] offset:576 sc1
	v_add_u32_e32 v142, 0x20000, v142
	global_load_dwordx4 v[158:161], v141, s[10:11] offset:576
	v_add_u32_e32 v141, 0x20000, v141
	s_waitcnt vmcnt(6)
	v_pk_fma_f32 v[162:163], v[16:17], v[166:167], v[162:163]
	v_pk_fma_f32 v[164:165], v[18:19], v[168:169], v[164:165]
	global_store_dwordx4 v142, v[162:165], s[12:13] offset:576 sc1
	v_add_u32_e32 v142, 0xa0000, v142
	global_load_dwordx4 v[162:165], v141, s[10:11] offset:576
	v_add_u32_e32 v141, 0x20000, v141
	s_waitcnt vmcnt(6)
	v_pk_fma_f32 v[150:151], v[12:13], v[166:167], v[150:151]
	v_pk_fma_f32 v[152:153], v[14:15], v[168:169], v[152:153]
	global_store_dwordx4 v142, v[150:153], s[12:13] offset:576 sc1
	v_add_u32_e32 v142, 0x20000, v142
	s_waitcnt vmcnt(5)
	v_pk_fma_f32 v[154:155], v[8:9], v[166:167], v[154:155]
	v_pk_fma_f32 v[156:157], v[10:11], v[168:169], v[156:157]
	global_store_dwordx4 v142, v[154:157], s[12:13] offset:576 sc1
	v_add_u32_e32 v142, 0x20000, v142
	s_waitcnt vmcnt(4)
	v_pk_fma_f32 v[158:159], v[4:5], v[166:167], v[158:159]
	v_pk_fma_f32 v[160:161], v[6:7], v[168:169], v[160:161]
	global_store_dwordx4 v142, v[158:161], s[12:13] offset:576 sc1
	v_add_u32_e32 v142, 0x20000, v142
	s_waitcnt vmcnt(3)
	v_pk_fma_f32 v[162:163], v[0:1], v[166:167], v[162:163]
	v_pk_fma_f32 v[164:165], v[2:3], v[168:169], v[164:165]
	global_store_dwordx4 v142, v[162:165], s[12:13] offset:576 sc1
	v_add_u32_e32 v142, 0x20000, v142
	s_and_b64 vcc, exec, s[6:7]
	s_cbranch_vccz .LBB0_843
	s_waitcnt vmcnt(0)
	s_cmpk_gt_u32 s20, 0xff
	s_cbranch_scc1 .LBB0_854
	s_barrier

.LBB0_1098:
	ds_read_b128 v[128:131], v221
	ds_read_b128 v[132:135], v221 offset:1024
	ds_read_b128 v[136:139], v221 offset:2048
	ds_read_b128 v[140:143], v221 offset:3072
	s_add_u32 s64, s62, 0x100
	s_addc_u32 s65, s63, 0
	s_cmpk_eq_i32 s76, 0x54
	s_cselect_b32 s5, s9, s65
	s_cselect_b32 s4, s8, s64
	s_cselect_b32 s67, s11, s1
	s_cselect_b32 s66, s10, s0
	s_add_i32 m0, s25, 0xc000
	ds_read_b128 v[144:147], v222
	ds_read_b128 v[148:151], v222 offset:1024
	ds_read_b128 v[152:155], v222 offset:2048
	ds_read_b128 v[156:159], v222 offset:3072
	ds_read_b128 v[160:163], v222 offset:4096
	ds_read_b128 v[176:179], v222 offset:5120
	ds_read_b128 v[180:183], v222 offset:6144
	ds_read_b128 v[184:187], v222 offset:7168
	global_load_lds_dwordx4 v168, s[62:63]
	s_add_i32 m0, s25, 0xe000
	s_nop 0
	global_load_lds_dwordx4 v170, s[62:63]
	s_waitcnt lgkmcnt(8)
	s_barrier
	s_waitcnt lgkmcnt(0)
	s_waitcnt lgkmcnt(0)
	v_mfma_f32_16x16x32_bf16 v[124:127], v[128:131], v[144:147], v[124:127]
	v_mfma_f32_16x16x32_bf16 v[100:103], v[136:139], v[144:147], v[100:103]
	v_mfma_f32_16x16x32_bf16 v[120:123], v[128:131], v[152:155], v[120:123]
	v_mfma_f32_16x16x32_bf16 v[96:99], v[136:139], v[152:155], v[96:99]
	v_mfma_f32_16x16x32_bf16 v[116:119], v[128:131], v[160:163], v[116:119]
	v_mfma_f32_16x16x32_bf16 v[92:95], v[136:139], v[160:163], v[92:95]
	v_mfma_f32_16x16x32_bf16 v[112:115], v[128:131], v[180:183], v[112:115]
	v_mfma_f32_16x16x32_bf16 v[84:87], v[136:139], v[180:183], v[84:87]
	v_mfma_f32_16x16x32_bf16 v[124:127], v[132:135], v[148:151], v[124:127]
	v_mfma_f32_16x16x32_bf16 v[100:103], v[140:143], v[148:151], v[100:103]
	v_mfma_f32_16x16x32_bf16 v[120:123], v[132:135], v[156:159], v[120:123]
	v_mfma_f32_16x16x32_bf16 v[96:99], v[140:143], v[156:159], v[96:99]
	v_mfma_f32_16x16x32_bf16 v[116:119], v[132:135], v[176:179], v[116:119]
	v_mfma_f32_16x16x32_bf16 v[92:95], v[140:143], v[176:179], v[92:95]
	v_mfma_f32_16x16x32_bf16 v[112:115], v[132:135], v[184:187], v[112:115]
	v_mfma_f32_16x16x32_bf16 v[84:87], v[140:143], v[184:187], v[84:87]
	s_barrier
	s_add_i32 s42, s41, s24
	s_add_u32 s98, s66, s18
	s_addc_u32 s99, s67, s19
	s_mov_b32 m0, s42
	ds_read_b128 v[188:191], v223
	ds_read_b128 v[192:195], v223 offset:1024
	ds_read_b128 v[196:199], v223 offset:2048
	ds_read_b128 v[200:203], v223 offset:3072
	global_load_lds_dwordx4 v166, s[66:67]
	s_add_i32 m0, s42, 0x2000
	s_nop 0
	global_load_lds_dwordx4 v164, s[66:67]
	s_barrier
	s_waitcnt lgkmcnt(0)
	s_waitcnt lgkmcnt(0)
	v_mfma_f32_16x16x32_bf16 v[72:75], v[188:191], v[144:147], v[72:75]
	v_mfma_f32_16x16x32_bf16 v[44:47], v[196:199], v[144:147], v[44:47]
	v_mfma_f32_16x16x32_bf16 v[64:67], v[188:191], v[152:155], v[64:67]
	v_mfma_f32_16x16x32_bf16 v[40:43], v[196:199], v[152:155], v[40:43]
	v_mfma_f32_16x16x32_bf16 v[56:59], v[188:191], v[160:163], v[56:59]
	v_mfma_f32_16x16x32_bf16 v[36:39], v[196:199], v[160:163], v[36:39]
	v_mfma_f32_16x16x32_bf16 v[48:51], v[188:191], v[180:183], v[48:51]
	v_mfma_f32_16x16x32_bf16 v[28:31], v[196:199], v[180:183], v[28:31]
	v_mfma_f32_16x16x32_bf16 v[72:75], v[192:195], v[148:151], v[72:75]
	v_mfma_f32_16x16x32_bf16 v[44:47], v[200:203], v[148:151], v[44:47]
	v_mfma_f32_16x16x32_bf16 v[64:67], v[192:195], v[156:159], v[64:67]
	v_mfma_f32_16x16x32_bf16 v[40:43], v[200:203], v[156:159], v[40:43]
	v_mfma_f32_16x16x32_bf16 v[56:59], v[192:195], v[176:179], v[56:59]
	v_mfma_f32_16x16x32_bf16 v[36:39], v[200:203], v[176:179], v[36:39]
	v_mfma_f32_16x16x32_bf16 v[48:51], v[192:195], v[184:187], v[48:51]
	v_mfma_f32_16x16x32_bf16 v[28:31], v[200:203], v[184:187], v[28:31]
	s_mov_b32 m0, s25
	s_add_u32 s100, s4, s18
	s_addc_u32 s101, s5, s19
	s_barrier
	ds_read_b128 v[144:147], v222 offset:16384
	ds_read_b128 v[148:151], v222 offset:17408
	ds_read_b128 v[152:155], v222 offset:18432
	ds_read_b128 v[156:159], v222 offset:19456
	ds_read_b128 v[160:163], v222 offset:20480
	ds_read_b128 v[176:179], v222 offset:21504
	ds_read_b128 v[180:183], v222 offset:22528
	ds_read_b128 v[184:187], v222 offset:23552
	global_load_lds_dwordx4 v166, s[4:5]
	s_mov_b32 m0, s28
	s_nop 0
	global_load_lds_dwordx4 v164, s[4:5]
	s_barrier
	s_waitcnt lgkmcnt(0)
	s_waitcnt lgkmcnt(0)
	v_mfma_f32_16x16x32_bf16 v[108:111], v[128:131], v[144:147], v[108:111]
	v_mfma_f32_16x16x32_bf16 v[76:79], v[136:139], v[144:147], v[76:79]
	v_mfma_f32_16x16x32_bf16 v[104:107], v[128:131], v[152:155], v[104:107]
	v_mfma_f32_16x16x32_bf16 v[68:71], v[136:139], v[152:155], v[68:71]
	v_mfma_f32_16x16x32_bf16 v[88:91], v[128:131], v[160:163], v[88:91]
	v_mfma_f32_16x16x32_bf16 v[60:63], v[136:139], v[160:163], v[60:63]
	v_mfma_f32_16x16x32_bf16 v[80:83], v[128:131], v[180:183], v[80:83]
	v_mfma_f32_16x16x32_bf16 v[52:55], v[136:139], v[180:183], v[52:55]
	v_mfma_f32_16x16x32_bf16 v[108:111], v[132:135], v[148:151], v[108:111]
	v_mfma_f32_16x16x32_bf16 v[76:79], v[140:143], v[148:151], v[76:79]
	v_mfma_f32_16x16x32_bf16 v[104:107], v[132:135], v[156:159], v[104:107]
	v_mfma_f32_16x16x32_bf16 v[68:71], v[140:143], v[156:159], v[68:71]
	v_mfma_f32_16x16x32_bf16 v[88:91], v[132:135], v[176:179], v[88:91]
	v_mfma_f32_16x16x32_bf16 v[60:63], v[140:143], v[176:179], v[60:63]
	v_mfma_f32_16x16x32_bf16 v[80:83], v[132:135], v[184:187], v[80:83]
	v_mfma_f32_16x16x32_bf16 v[52:55], v[140:143], v[184:187], v[52:55]
	s_barrier
	s_add_u32 s42, s66, 0x160000
	s_addc_u32 s43, s67, 0
	s_add_i32 s44, s53, s24
	s_mov_b32 m0, s44
	s_nop 0
	global_load_lds_dwordx4 v166, s[42:43]
	s_add_i32 m0, s44, 0x2000
	s_nop 0
	global_load_lds_dwordx4 v164, s[42:43]
	s_waitcnt vmcnt(6)
	s_barrier
	v_mfma_f32_16x16x32_bf16 v[32:35], v[188:191], v[144:147], v[32:35]
	v_mfma_f32_16x16x32_bf16 v[12:15], v[196:199], v[144:147], v[12:15]
	v_mfma_f32_16x16x32_bf16 v[24:27], v[188:191], v[152:155], v[24:27]
	v_mfma_f32_16x16x32_bf16 v[8:11], v[196:199], v[152:155], v[8:11]
	v_mfma_f32_16x16x32_bf16 v[20:23], v[188:191], v[160:163], v[20:23]
	v_mfma_f32_16x16x32_bf16 v[4:7], v[196:199], v[160:163], v[4:7]
	v_mfma_f32_16x16x32_bf16 v[16:19], v[188:191], v[180:183], v[16:19]
	v_mfma_f32_16x16x32_bf16 v[0:3], v[196:199], v[180:183], v[0:3]
	v_mfma_f32_16x16x32_bf16 v[32:35], v[192:195], v[148:151], v[32:35]
	v_mfma_f32_16x16x32_bf16 v[12:15], v[200:203], v[148:151], v[12:15]
	v_mfma_f32_16x16x32_bf16 v[24:27], v[192:195], v[156:159], v[24:27]
	v_mfma_f32_16x16x32_bf16 v[8:11], v[200:203], v[156:159], v[8:11]
	v_mfma_f32_16x16x32_bf16 v[20:23], v[192:195], v[176:179], v[20:23]
	v_mfma_f32_16x16x32_bf16 v[4:7], v[200:203], v[176:179], v[4:7]
	v_mfma_f32_16x16x32_bf16 v[16:19], v[192:195], v[184:187], v[16:19]
	v_mfma_f32_16x16x32_bf16 v[0:3], v[200:203], v[184:187], v[0:3]
	s_add_i32 s42, 0, 0x18000
	v_add_u32_e32 v140, s42, v219
	s_barrier
	ds_read_b128 v[128:131], v140
	ds_read_b128 v[132:135], v140 offset:1024
	ds_read_b128 v[136:139], v140 offset:2048
	ds_read_b128 v[140:143], v140 offset:3072
	s_add_u32 s4, s4, 0x160000
	s_addc_u32 s5, s5, 0
	s_mov_b32 m0, s29
	ds_read_b128 v[144:147], v222 offset:32768
	ds_read_b128 v[148:151], v222 offset:33792
	ds_read_b128 v[152:155], v222 offset:34816
	ds_read_b128 v[156:159], v222 offset:35840
	ds_read_b128 v[160:163], v222 offset:36864
	ds_read_b128 v[176:179], v222 offset:37888
	ds_read_b128 v[180:183], v222 offset:38912
	ds_read_b128 v[184:187], v222 offset:39936
	global_load_lds_dwordx4 v166, s[4:5]
	s_mov_b32 m0, s33
	s_nop 0
	global_load_lds_dwordx4 v164, s[4:5]
	s_waitcnt lgkmcnt(8)
	s_barrier
	s_waitcnt lgkmcnt(0)
	s_waitcnt lgkmcnt(0)
	v_mfma_f32_16x16x32_bf16 v[124:127], v[128:131], v[144:147], v[124:127]
	v_mfma_f32_16x16x32_bf16 v[100:103], v[136:139], v[144:147], v[100:103]
	v_mfma_f32_16x16x32_bf16 v[120:123], v[128:131], v[152:155], v[120:123]
	v_mfma_f32_16x16x32_bf16 v[96:99], v[136:139], v[152:155], v[96:99]
	v_mfma_f32_16x16x32_bf16 v[116:119], v[128:131], v[160:163], v[116:119]
	v_mfma_f32_16x16x32_bf16 v[92:95], v[136:139], v[160:163], v[92:95]
	v_mfma_f32_16x16x32_bf16 v[112:115], v[128:131], v[180:183], v[112:115]
	v_mfma_f32_16x16x32_bf16 v[84:87], v[136:139], v[180:183], v[84:87]
	v_mfma_f32_16x16x32_bf16 v[124:127], v[132:135], v[148:151], v[124:127]
	v_mfma_f32_16x16x32_bf16 v[100:103], v[140:143], v[148:151], v[100:103]
	v_mfma_f32_16x16x32_bf16 v[120:123], v[132:135], v[156:159], v[120:123]
	v_mfma_f32_16x16x32_bf16 v[96:99], v[140:143], v[156:159], v[96:99]
	v_mfma_f32_16x16x32_bf16 v[116:119], v[132:135], v[176:179], v[116:119]
	v_mfma_f32_16x16x32_bf16 v[92:95], v[140:143], v[176:179], v[92:95]
	v_mfma_f32_16x16x32_bf16 v[112:115], v[132:135], v[184:187], v[112:115]
	v_mfma_f32_16x16x32_bf16 v[84:87], v[140:143], v[184:187], v[84:87]
	s_barrier
	s_add_i32 s43, 0, 0x1c000
	s_add_i32 s4, s42, s24
	v_add_u32_e32 v200, s43, v219
	s_mov_b32 m0, s4
	ds_read_b128 v[188:191], v200
	ds_read_b128 v[192:195], v200 offset:1024
	ds_read_b128 v[196:199], v200 offset:2048
	ds_read_b128 v[200:203], v200 offset:3072
	global_load_lds_dwordx4 v166, s[98:99]
	s_add_i32 m0, s4, 0x2000
	s_nop 0
	global_load_lds_dwordx4 v164, s[98:99]
	s_barrier
	s_waitcnt lgkmcnt(0)
	s_waitcnt lgkmcnt(0)
	v_mfma_f32_16x16x32_bf16 v[72:75], v[188:191], v[144:147], v[72:75]
	v_mfma_f32_16x16x32_bf16 v[44:47], v[196:199], v[144:147], v[44:47]
	v_mfma_f32_16x16x32_bf16 v[64:67], v[188:191], v[152:155], v[64:67]
	v_mfma_f32_16x16x32_bf16 v[40:43], v[196:199], v[152:155], v[40:43]
	v_mfma_f32_16x16x32_bf16 v[56:59], v[188:191], v[160:163], v[56:59]
	v_mfma_f32_16x16x32_bf16 v[36:39], v[196:199], v[160:163], v[36:39]
	v_mfma_f32_16x16x32_bf16 v[48:51], v[188:191], v[180:183], v[48:51]
	v_mfma_f32_16x16x32_bf16 v[28:31], v[196:199], v[180:183], v[28:31]
	v_mfma_f32_16x16x32_bf16 v[72:75], v[192:195], v[148:151], v[72:75]
	v_mfma_f32_16x16x32_bf16 v[44:47], v[200:203], v[148:151], v[44:47]
	v_mfma_f32_16x16x32_bf16 v[64:67], v[192:195], v[156:159], v[64:67]
	v_mfma_f32_16x16x32_bf16 v[40:43], v[200:203], v[156:159], v[40:43]
	v_mfma_f32_16x16x32_bf16 v[56:59], v[192:195], v[176:179], v[56:59]
	v_mfma_f32_16x16x32_bf16 v[36:39], v[200:203], v[176:179], v[36:39]
	v_mfma_f32_16x16x32_bf16 v[48:51], v[192:195], v[184:187], v[48:51]
	v_mfma_f32_16x16x32_bf16 v[28:31], v[200:203], v[184:187], v[28:31]
	s_mov_b32 m0, s37
	s_barrier
	ds_read_b128 v[144:147], v222 offset:49152
	ds_read_b128 v[148:151], v222 offset:50176
	ds_read_b128 v[152:155], v222 offset:51200
	ds_read_b128 v[156:159], v222 offset:52224
	ds_read_b128 v[160:163], v222 offset:53248
	ds_read_b128 v[176:179], v222 offset:54272
	ds_read_b128 v[180:183], v222 offset:55296
	ds_read_b128 v[184:187], v222 offset:56320
	global_load_lds_dwordx4 v166, s[100:101]
	s_mov_b32 m0, s40
	s_nop 0
	global_load_lds_dwordx4 v164, s[100:101]
	s_barrier
	s_waitcnt lgkmcnt(0)
	s_waitcnt lgkmcnt(0)
	v_mfma_f32_16x16x32_bf16 v[108:111], v[128:131], v[144:147], v[108:111]
	v_mfma_f32_16x16x32_bf16 v[76:79], v[136:139], v[144:147], v[76:79]
	v_mfma_f32_16x16x32_bf16 v[104:107], v[128:131], v[152:155], v[104:107]
	v_mfma_f32_16x16x32_bf16 v[68:71], v[136:139], v[152:155], v[68:71]
	v_mfma_f32_16x16x32_bf16 v[88:91], v[128:131], v[160:163], v[88:91]
	v_mfma_f32_16x16x32_bf16 v[60:63], v[136:139], v[160:163], v[60:63]
	v_mfma_f32_16x16x32_bf16 v[80:83], v[128:131], v[180:183], v[80:83]
	v_mfma_f32_16x16x32_bf16 v[52:55], v[136:139], v[180:183], v[52:55]
	v_mfma_f32_16x16x32_bf16 v[108:111], v[132:135], v[148:151], v[108:111]
	v_mfma_f32_16x16x32_bf16 v[76:79], v[140:143], v[148:151], v[76:79]
	v_mfma_f32_16x16x32_bf16 v[104:107], v[132:135], v[156:159], v[104:107]
	v_mfma_f32_16x16x32_bf16 v[68:71], v[140:143], v[156:159], v[68:71]
	v_mfma_f32_16x16x32_bf16 v[88:91], v[132:135], v[176:179], v[88:91]
	v_mfma_f32_16x16x32_bf16 v[60:63], v[140:143], v[176:179], v[60:63]
	v_mfma_f32_16x16x32_bf16 v[80:83], v[132:135], v[184:187], v[80:83]
	v_mfma_f32_16x16x32_bf16 v[52:55], v[140:143], v[184:187], v[52:55]
	s_barrier
	s_add_u32 s4, s66, 0x160080
	s_addc_u32 s5, s67, 0
	s_add_i32 s42, s43, s24
	s_mov_b32 m0, s42
	s_nop 0
	global_load_lds_dwordx4 v166, s[4:5]
	s_add_i32 m0, s42, 0x2000
	s_nop 0
	global_load_lds_dwordx4 v164, s[4:5]
	s_waitcnt vmcnt(6)
	s_barrier
	v_mfma_f32_16x16x32_bf16 v[32:35], v[188:191], v[144:147], v[32:35]
	v_mfma_f32_16x16x32_bf16 v[12:15], v[196:199], v[144:147], v[12:15]
	v_mfma_f32_16x16x32_bf16 v[24:27], v[188:191], v[152:155], v[24:27]
	v_mfma_f32_16x16x32_bf16 v[8:11], v[196:199], v[152:155], v[8:11]
	v_mfma_f32_16x16x32_bf16 v[20:23], v[188:191], v[160:163], v[20:23]
	v_mfma_f32_16x16x32_bf16 v[4:7], v[196:199], v[160:163], v[4:7]
	v_mfma_f32_16x16x32_bf16 v[16:19], v[188:191], v[180:183], v[16:19]
	v_mfma_f32_16x16x32_bf16 v[0:3], v[196:199], v[180:183], v[0:3]
	v_mfma_f32_16x16x32_bf16 v[32:35], v[192:195], v[148:151], v[32:35]
	v_mfma_f32_16x16x32_bf16 v[12:15], v[200:203], v[148:151], v[12:15]
	v_mfma_f32_16x16x32_bf16 v[24:27], v[192:195], v[156:159], v[24:27]
	v_mfma_f32_16x16x32_bf16 v[8:11], v[200:203], v[156:159], v[8:11]
	v_mfma_f32_16x16x32_bf16 v[20:23], v[192:195], v[176:179], v[20:23]
	v_mfma_f32_16x16x32_bf16 v[4:7], v[200:203], v[176:179], v[4:7]
	v_mfma_f32_16x16x32_bf16 v[16:19], v[192:195], v[184:187], v[16:19]
	v_mfma_f32_16x16x32_bf16 v[0:3], v[200:203], v[184:187], v[0:3]
	s_add_i32 s76, s76, 2
	s_add_u32 s0, s0, 0x100
	s_addc_u32 s1, s1, 0
	s_cmpk_gt_u32 s76, 0x55
	s_mov_b64 s[62:63], s[64:65]
	s_barrier
	s_cbranch_scc0 .LBB0_1098
	v_lshl_add_u32 v144, s74, 8, v218
	v_lshl_or_b32 v184, s75, 8, v220
	v_ashrrev_i32_e32 v145, 31, v144
	v_ashrrev_i32_e32 v185, 31, v184
	v_lshlrev_b64 v[132:133], 13, v[144:145]
	v_lshlrev_b64 v[146:147], 2, v[184:185]
	v_lshl_add_u64 v[132:133], s[12:13], 0, v[132:133]
	v_lshl_add_u64 v[176:177], v[132:133], 0, v[146:147]
	v_or_b32_e32 v136, 16, v144
	v_add_co_u32_e32 v186, vcc, s68, v176
	v_ashrrev_i32_e32 v137, 31, v136
	v_or_b32_e32 v140, 32, v144
	v_or_b32_e32 v144, 48, v144
	v_addc_co_u32_e32 v187, vcc, 0, v177, vcc
	v_lshlrev_b64 v[136:137], 13, v[136:137]
	v_ashrrev_i32_e32 v141, 31, v140
	v_ashrrev_i32_e32 v145, 31, v144
	v_add_co_u32_e32 v190, vcc, s69, v176
	v_lshl_add_u64 v[128:129], s[16:17], 0, v[146:147]
	v_lshl_add_u64 v[136:137], s[12:13], 0, v[136:137]
	v_lshlrev_b64 v[140:141], 13, v[140:141]
	v_lshlrev_b64 v[144:145], 13, v[144:145]
	v_addc_co_u32_e32 v191, vcc, 0, v177, vcc
	global_load_dwordx4 v[128:131], v[128:129], off
	v_lshl_add_u64 v[178:179], v[136:137], 0, v[146:147]
	global_load_dwordx4 v[132:135], v[176:177], off
	global_load_dwordx4 v[136:139], v[178:179], off
	v_lshl_add_u64 v[140:141], s[12:13], 0, v[140:141]
	v_lshl_add_u64 v[144:145], s[12:13], 0, v[144:145]
	v_add_co_u32_e32 v192, vcc, s70, v176
	v_lshl_add_u64 v[180:181], v[140:141], 0, v[146:147]
	v_lshl_add_u64 v[182:183], v[144:145], 0, v[146:147]
	v_addc_co_u32_e32 v193, vcc, 0, v177, vcc
	global_load_dwordx4 v[140:143], v[180:181], off
	global_load_dwordx4 v[144:147], v[182:183], off
	global_load_dwordx4 v[148:151], v[186:187], off
	global_load_dwordx4 v[160:163], v[190:191], off
	global_load_dwordx4 v[156:159], v[192:193], off
	v_add_co_u32_e32 v188, vcc, s71, v176
	v_pk_add_f32 v[212:213], v[126:127], 0 op_sel_hi:[1,0]
	s_nop 0
	v_addc_co_u32_e32 v189, vcc, 0, v177, vcc
	global_load_dwordx4 v[152:155], v[188:189], off
	v_pk_add_f32 v[214:215], v[124:125], 0 op_sel_hi:[1,0]
	v_pk_add_f32 v[126:127], v[122:123], 0 op_sel_hi:[1,0]
	v_pk_add_f32 v[194:195], v[120:121], 0 op_sel_hi:[1,0]
	v_pk_add_f32 v[196:197], v[118:119], 0 op_sel_hi:[1,0]
	v_pk_add_f32 v[198:199], v[116:117], 0 op_sel_hi:[1,0]
	v_pk_add_f32 v[200:201], v[114:115], 0 op_sel_hi:[1,0]
	v_pk_add_f32 v[202:203], v[112:113], 0 op_sel_hi:[1,0]
	v_pk_add_f32 v[204:205], v[110:111], 0 op_sel_hi:[1,0]
	v_pk_add_f32 v[206:207], v[108:109], 0 op_sel_hi:[1,0]
	v_pk_add_f32 v[208:209], v[106:107], 0 op_sel_hi:[1,0]
	v_pk_add_f32 v[210:211], v[104:105], 0 op_sel_hi:[1,0]
	v_lshl_add_u64 v[120:121], v[176:177], 0, s[20:21]
	v_lshl_add_u64 v[122:123], v[176:177], 0, s[46:47]
	global_load_dwordx4 v[104:107], v[176:177], off offset:64
	global_load_dwordx4 v[108:111], v[178:179], off offset:64
	global_load_dwordx4 v[112:115], v[180:181], off offset:64
	global_load_dwordx4 v[116:119], v[182:183], off offset:64
	global_load_dwordx4 v[224:227], v[120:121], off offset:576
	global_load_dwordx4 v[228:231], v[122:123], off offset:576
	v_lshl_add_u64 v[124:125], v[176:177], 0, s[60:61]
	v_pk_add_f32 v[102:103], v[102:103], 0 op_sel_hi:[1,0]
	v_pk_add_f32 v[100:101], v[100:101], 0 op_sel_hi:[1,0]
	v_pk_add_f32 v[98:99], v[98:99], 0 op_sel_hi:[1,0]
	v_pk_add_f32 v[96:97], v[96:97], 0 op_sel_hi:[1,0]
	v_pk_add_f32 v[74:75], v[74:75], 0 op_sel_hi:[1,0]
	v_pk_add_f32 v[72:73], v[72:73], 0 op_sel_hi:[1,0]
	v_pk_add_f32 v[66:67], v[66:67], 0 op_sel_hi:[1,0]
	v_pk_add_f32 v[64:65], v[64:65], 0 op_sel_hi:[1,0]
	v_pk_add_f32 v[58:59], v[58:59], 0 op_sel_hi:[1,0]
	v_pk_add_f32 v[56:57], v[56:57], 0 op_sel_hi:[1,0]
	v_pk_add_f32 v[46:47], v[46:47], 0 op_sel_hi:[1,0]
	v_pk_add_f32 v[44:45], v[44:45], 0 op_sel_hi:[1,0]
	v_pk_add_f32 v[42:43], v[42:43], 0 op_sel_hi:[1,0]
	v_pk_add_f32 v[40:41], v[40:41], 0 op_sel_hi:[1,0]
	v_pk_add_f32 v[38:39], v[38:39], 0 op_sel_hi:[1,0]
	v_pk_add_f32 v[36:37], v[36:37], 0 op_sel_hi:[1,0]
	v_pk_add_f32 v[30:31], v[30:31], 0 op_sel_hi:[1,0]
	v_pk_add_f32 v[28:29], v[28:29], 0 op_sel_hi:[1,0]
	s_and_b64 vcc, exec, s[6:7]
	s_mov_b32 s75, s72
	s_mov_b32 s74, s73
	s_mov_b64 s[64:65], s[10:11]
	s_mov_b64 s[62:63], s[8:9]
	s_waitcnt vmcnt(0)
	v_pk_fma_f32 v[134:135], v[212:213], v[130:131], v[134:135]
	v_pk_fma_f32 v[132:133], v[214:215], v[128:129], v[132:133]
	global_store_dwordx4 v[176:177], v[132:135], off sc1
	s_nop 1
	v_pk_fma_f32 v[134:135], v[126:127], v[130:131], v[138:139]
	v_pk_fma_f32 v[132:133], v[194:195], v[128:129], v[136:137]
	v_pk_add_f32 v[126:127], v[90:91], 0 op_sel_hi:[1,0]
	v_pk_fma_f32 v[138:139], v[196:197], v[130:131], v[142:143]
	v_pk_fma_f32 v[136:137], v[198:199], v[128:129], v[140:141]
	v_pk_fma_f32 v[142:143], v[200:201], v[130:131], v[146:147]
	v_pk_fma_f32 v[140:141], v[202:203], v[128:129], v[144:145]
	v_pk_fma_f32 v[146:147], v[204:205], v[130:131], v[150:151]
	v_pk_fma_f32 v[144:145], v[206:207], v[128:129], v[148:149]
	v_pk_fma_f32 v[150:151], v[208:209], v[130:131], v[162:163]
	v_pk_fma_f32 v[148:149], v[210:211], v[128:129], v[160:161]
	global_store_dwordx4 v[178:179], v[132:135], off sc1
	global_store_dwordx4 v[180:181], v[136:139], off sc1
	global_store_dwordx4 v[182:183], v[140:143], off sc1
	global_store_dwordx4 v[186:187], v[144:147], off sc1
	global_store_dwordx4 v[190:191], v[148:151], off sc1
	v_pk_add_f32 v[132:133], v[88:89], 0 op_sel_hi:[1,0]
	v_pk_fma_f32 v[134:135], v[126:127], v[130:131], v[158:159]
	v_pk_fma_f32 v[132:133], v[132:133], v[128:129], v[156:157]
	v_pk_add_f32 v[126:127], v[82:83], 0 op_sel_hi:[1,0]
	global_store_dwordx4 v[192:193], v[132:135], off sc1
	v_pk_fma_f32 v[130:131], v[126:127], v[130:131], v[154:155]
	v_or_b32_e32 v126, 16, v184
	v_pk_add_f32 v[132:133], v[80:81], 0 op_sel_hi:[1,0]
	v_ashrrev_i32_e32 v127, 31, v126
	v_pk_fma_f32 v[128:129], v[132:133], v[128:129], v[152:153]
	v_lshl_add_u64 v[146:147], v[176:177], 0, s[14:15]
	global_store_dwordx4 v[188:189], v[128:131], off sc1
	v_lshl_add_u64 v[126:127], v[126:127], 2, s[16:17]
	global_load_dwordx4 v[88:91], v[124:125], off offset:576
	global_load_dwordx4 v[80:83], v[146:147], off offset:576
	s_nop 0
	global_load_dwordx4 v[126:129], v[126:127], off
	s_nop 0
	global_load_dwordx4 v[130:133], v[120:121], off offset:64
	global_load_dwordx4 v[134:137], v[122:123], off offset:64
	global_load_dwordx4 v[138:141], v[124:125], off offset:64
	global_load_dwordx4 v[142:145], v[146:147], off offset:64
	v_pk_add_f32 v[192:193], v[52:53], 0 op_sel_hi:[1,0]
	v_or_b32_e32 v52, 0x80, v184
	v_pk_add_f32 v[148:149], v[94:95], 0 op_sel_hi:[1,0]
	v_pk_add_f32 v[150:151], v[92:93], 0 op_sel_hi:[1,0]
	v_pk_add_f32 v[152:153], v[86:87], 0 op_sel_hi:[1,0]
	v_pk_add_f32 v[154:155], v[84:85], 0 op_sel_hi:[1,0]
	v_pk_add_f32 v[156:157], v[78:79], 0 op_sel_hi:[1,0]
	v_pk_add_f32 v[158:159], v[76:77], 0 op_sel_hi:[1,0]
	v_pk_add_f32 v[160:161], v[70:71], 0 op_sel_hi:[1,0]
	v_pk_add_f32 v[162:163], v[68:69], 0 op_sel_hi:[1,0]
	v_pk_add_f32 v[186:187], v[62:63], 0 op_sel_hi:[1,0]
	v_pk_add_f32 v[188:189], v[60:61], 0 op_sel_hi:[1,0]
	v_pk_add_f32 v[190:191], v[54:55], 0 op_sel_hi:[1,0]
	v_ashrrev_i32_e32 v53, 31, v52
	v_lshl_add_u64 v[194:195], v[52:53], 2, s[16:17]
	global_load_dwordx4 v[52:55], v[176:177], off offset:512
	global_load_dwordx4 v[60:63], v[120:121], off offset:512
	global_load_dwordx4 v[68:71], v[122:123], off offset:512
	global_load_dwordx4 v[76:79], v[124:125], off offset:512
	global_load_dwordx4 v[84:87], v[146:147], off offset:512
	s_waitcnt vmcnt(0)
	v_pk_fma_f32 v[94:95], v[102:103], v[128:129], v[106:107]
	v_pk_fma_f32 v[92:93], v[100:101], v[126:127], v[104:105]
	v_pk_fma_f32 v[98:99], v[98:99], v[128:129], v[110:111]
	v_pk_fma_f32 v[96:97], v[96:97], v[126:127], v[108:109]
	v_pk_fma_f32 v[102:103], v[148:149], v[128:129], v[114:115]
	v_pk_fma_f32 v[100:101], v[150:151], v[126:127], v[112:113]
	v_pk_fma_f32 v[106:107], v[152:153], v[128:129], v[118:119]
	v_pk_fma_f32 v[104:105], v[154:155], v[126:127], v[116:117]
	v_pk_fma_f32 v[110:111], v[156:157], v[128:129], v[132:133]
	v_pk_fma_f32 v[108:109], v[158:159], v[126:127], v[130:131]
	v_pk_fma_f32 v[114:115], v[160:161], v[128:129], v[136:137]
	v_pk_fma_f32 v[112:113], v[162:163], v[126:127], v[134:135]
	v_pk_fma_f32 v[118:119], v[186:187], v[128:129], v[140:141]
	v_pk_fma_f32 v[116:117], v[188:189], v[126:127], v[138:139]
	v_pk_fma_f32 v[128:129], v[190:191], v[128:129], v[144:145]
	v_pk_fma_f32 v[126:127], v[192:193], v[126:127], v[142:143]
	global_store_dwordx4 v[176:177], v[92:95], off offset:64 sc1
	global_store_dwordx4 v[178:179], v[96:99], off offset:64 sc1
	global_store_dwordx4 v[180:181], v[100:103], off offset:64 sc1
	global_store_dwordx4 v[182:183], v[104:107], off offset:64 sc1
	global_store_dwordx4 v[120:121], v[108:111], off offset:64 sc1
	global_store_dwordx4 v[122:123], v[112:115], off offset:64 sc1
	global_store_dwordx4 v[124:125], v[116:119], off offset:64 sc1
	global_store_dwordx4 v[146:147], v[126:129], off offset:64 sc1
	global_load_dwordx4 v[92:95], v[194:195], off
	global_load_dwordx4 v[96:99], v[178:179], off offset:512
	global_load_dwordx4 v[100:103], v[180:181], off offset:512
	global_load_dwordx4 v[104:107], v[182:183], off offset:512
	v_pk_add_f32 v[132:133], v[16:17], 0 op_sel_hi:[1,0]
	v_or_b32_e32 v16, 0x90, v184
	v_pk_add_f32 v[108:109], v[50:51], 0 op_sel_hi:[1,0]
	v_pk_add_f32 v[110:111], v[48:49], 0 op_sel_hi:[1,0]
	v_pk_add_f32 v[112:113], v[34:35], 0 op_sel_hi:[1,0]
	v_pk_add_f32 v[114:115], v[32:33], 0 op_sel_hi:[1,0]
	v_pk_add_f32 v[116:117], v[26:27], 0 op_sel_hi:[1,0]
	v_pk_add_f32 v[118:119], v[24:25], 0 op_sel_hi:[1,0]
	v_pk_add_f32 v[126:127], v[22:23], 0 op_sel_hi:[1,0]
	v_pk_add_f32 v[128:129], v[20:21], 0 op_sel_hi:[1,0]
	v_pk_add_f32 v[130:131], v[18:19], 0 op_sel_hi:[1,0]
	v_ashrrev_i32_e32 v17, 31, v16
	v_lshl_add_u64 v[134:135], v[16:17], 2, s[16:17]
	global_load_dwordx4 v[16:19], v[176:177], off offset:576
	global_load_dwordx4 v[20:23], v[178:179], off offset:576
	global_load_dwordx4 v[24:27], v[180:181], off offset:576
	global_load_dwordx4 v[32:35], v[182:183], off offset:576
	s_waitcnt vmcnt(0)
	v_pk_fma_f32 v[50:51], v[74:75], v[94:95], v[54:55]
	v_pk_fma_f32 v[48:49], v[72:73], v[92:93], v[52:53]
	v_pk_fma_f32 v[54:55], v[66:67], v[94:95], v[98:99]
	v_pk_fma_f32 v[52:53], v[64:65], v[92:93], v[96:97]
	v_pk_fma_f32 v[58:59], v[58:59], v[94:95], v[102:103]
	v_pk_fma_f32 v[56:57], v[56:57], v[92:93], v[100:101]
	v_pk_fma_f32 v[66:67], v[108:109], v[94:95], v[106:107]
	v_pk_fma_f32 v[64:65], v[110:111], v[92:93], v[104:105]
	v_pk_fma_f32 v[62:63], v[112:113], v[94:95], v[62:63]
	v_pk_fma_f32 v[60:61], v[114:115], v[92:93], v[60:61]
	v_pk_fma_f32 v[70:71], v[116:117], v[94:95], v[70:71]
	v_pk_fma_f32 v[68:69], v[118:119], v[92:93], v[68:69]
	v_pk_fma_f32 v[74:75], v[126:127], v[94:95], v[78:79]
	v_pk_fma_f32 v[72:73], v[128:129], v[92:93], v[76:77]
	v_pk_fma_f32 v[78:79], v[130:131], v[94:95], v[86:87]
	v_pk_fma_f32 v[76:77], v[132:133], v[92:93], v[84:85]
	global_store_dwordx4 v[176:177], v[48:51], off offset:512 sc1
	global_store_dwordx4 v[178:179], v[52:55], off offset:512 sc1
	global_store_dwordx4 v[180:181], v[56:59], off offset:512 sc1
	global_store_dwordx4 v[182:183], v[64:67], off offset:512 sc1
	global_store_dwordx4 v[120:121], v[60:63], off offset:512 sc1
	global_store_dwordx4 v[122:123], v[68:71], off offset:512 sc1
	global_store_dwordx4 v[124:125], v[72:75], off offset:512 sc1
	global_store_dwordx4 v[146:147], v[76:79], off offset:512 sc1
	global_load_dwordx4 v[48:51], v[134:135], off
	v_pk_add_f32 v[52:53], v[14:15], 0 op_sel_hi:[1,0]
	v_pk_add_f32 v[54:55], v[12:13], 0 op_sel_hi:[1,0]
	v_pk_add_f32 v[56:57], v[10:11], 0 op_sel_hi:[1,0]
	v_pk_add_f32 v[58:59], v[8:9], 0 op_sel_hi:[1,0]
	v_pk_add_f32 v[60:61], v[6:7], 0 op_sel_hi:[1,0]
	v_pk_add_f32 v[62:63], v[4:5], 0 op_sel_hi:[1,0]
	v_pk_add_f32 v[64:65], v[2:3], 0 op_sel_hi:[1,0]
	v_pk_add_f32 v[66:67], v[0:1], 0 op_sel_hi:[1,0]
	s_waitcnt vmcnt(0)
	v_pk_fma_f32 v[2:3], v[46:47], v[50:51], v[18:19]
	v_pk_fma_f32 v[0:1], v[44:45], v[48:49], v[16:17]
	v_pk_fma_f32 v[6:7], v[42:43], v[50:51], v[22:23]
	v_pk_fma_f32 v[4:5], v[40:41], v[48:49], v[20:21]
	v_pk_fma_f32 v[10:11], v[38:39], v[50:51], v[26:27]
	v_pk_fma_f32 v[8:9], v[36:37], v[48:49], v[24:25]
	v_pk_fma_f32 v[14:15], v[30:31], v[50:51], v[34:35]
	v_pk_fma_f32 v[12:13], v[28:29], v[48:49], v[32:33]
	v_pk_fma_f32 v[18:19], v[52:53], v[50:51], v[226:227]
	v_pk_fma_f32 v[16:17], v[54:55], v[48:49], v[224:225]
	v_pk_fma_f32 v[22:23], v[56:57], v[50:51], v[230:231]
	v_pk_fma_f32 v[20:21], v[58:59], v[48:49], v[228:229]
	v_pk_fma_f32 v[26:27], v[60:61], v[50:51], v[90:91]
	v_pk_fma_f32 v[24:25], v[62:63], v[48:49], v[88:89]
	v_pk_fma_f32 v[30:31], v[64:65], v[50:51], v[82:83]
	v_pk_fma_f32 v[28:29], v[66:67], v[48:49], v[80:81]
	global_store_dwordx4 v[176:177], v[0:3], off offset:576 sc1
	global_store_dwordx4 v[178:179], v[4:7], off offset:576 sc1
	global_store_dwordx4 v[180:181], v[8:11], off offset:576 sc1
	global_store_dwordx4 v[182:183], v[12:15], off offset:576 sc1
	global_store_dwordx4 v[120:121], v[16:19], off offset:576 sc1
	global_store_dwordx4 v[122:123], v[20:23], off offset:576 sc1
	global_store_dwordx4 v[124:125], v[24:27], off offset:576 sc1
	global_store_dwordx4 v[146:147], v[28:31], off offset:576 sc1
	s_cbranch_vccz .LBB0_1087
	s_waitcnt vmcnt(0)
	s_cmpk_gt_u32 s23, 0xff
	s_cbranch_scc1 .LBB0_1102
	s_barrier

.LBB0_1536:
	v_lshl_add_u32 v156, s66, 8, v162
	v_ashrrev_i32_e32 v157, 31, v156
	v_lshlrev_b64 v[150:151], 13, v[156:157]
	v_lshl_add_u64 v[150:151], s[12:13], 0, v[150:151]
	v_lshlrev_b64 v[176:177], 2, v[160:161]
	v_lshl_add_u64 v[150:151], v[150:151], 0, v[176:177]
	v_add_co_u32_e32 v200, vcc, s67, v150
	v_or_b32_e32 v152, 16, v156
	s_nop 0
	v_addc_co_u32_e32 v201, vcc, 0, v151, vcc
	v_add_co_u32_e32 v202, vcc, s72, v150
	v_or_b32_e32 v154, 32, v156
	s_nop 0
	v_addc_co_u32_e32 v203, vcc, 0, v151, vcc
	v_ashrrev_i32_e32 v153, 31, v152
	v_ashrrev_i32_e32 v155, 31, v154
	v_or_b32_e32 v156, 48, v156
	v_add_co_u32_e32 v204, vcc, s73, v150
	v_lshlrev_b64 v[152:153], 13, v[152:153]
	v_lshlrev_b64 v[154:155], 13, v[154:155]
	v_ashrrev_i32_e32 v157, 31, v156
	v_addc_co_u32_e32 v205, vcc, 0, v151, vcc
	v_lshl_add_u64 v[152:153], s[12:13], 0, v[152:153]
	v_lshl_add_u64 v[154:155], s[12:13], 0, v[154:155]
	v_lshlrev_b64 v[156:157], 13, v[156:157]
	v_add_co_u32_e32 v206, vcc, s74, v150
	v_lshl_add_u64 v[152:153], v[152:153], 0, v[176:177]
	global_load_dwordx4 v[168:171], v[150:151], off
	global_load_dwordx4 v[172:175], v[152:153], off
	v_lshl_add_u64 v[154:155], v[154:155], 0, v[176:177]
	v_lshl_add_u64 v[156:157], s[12:13], 0, v[156:157]
	v_addc_co_u32_e32 v207, vcc, 0, v151, vcc
	v_lshl_add_u64 v[156:157], v[156:157], 0, v[176:177]
	global_load_dwordx4 v[176:179], v[154:155], off
	global_load_dwordx4 v[180:183], v[156:157], off
	global_load_dwordx4 v[184:187], v[200:201], off
	global_load_dwordx4 v[188:191], v[202:203], off
	global_load_dwordx4 v[192:195], v[204:205], off
	global_load_dwordx4 v[196:199], v[206:207], off
	s_waitcnt vmcnt(0) lgkmcnt(0)
	v_pk_add_f32 v[126:127], v[126:127], v[136:137]
	v_pk_add_f32 v[124:125], v[124:125], v[134:135]
	v_pk_add_f32 v[122:123], v[122:123], v[136:137]
	v_pk_add_f32 v[120:121], v[120:121], v[134:135]
	v_pk_add_f32 v[118:119], v[118:119], v[136:137]
	v_pk_add_f32 v[116:117], v[116:117], v[134:135]
	v_pk_add_f32 v[114:115], v[114:115], v[136:137]
	v_pk_add_f32 v[112:113], v[112:113], v[134:135]
	v_pk_add_f32 v[110:111], v[110:111], v[136:137]
	v_pk_add_f32 v[108:109], v[108:109], v[134:135]
	v_pk_add_f32 v[208:209], v[106:107], v[136:137]
	v_pk_add_f32 v[210:211], v[104:105], v[134:135]
	v_pk_add_f32 v[212:213], v[102:103], v[136:137]
	v_pk_add_f32 v[214:215], v[100:101], v[134:135]
	v_pk_add_f32 v[136:137], v[98:99], v[136:137]
	v_pk_add_f32 v[134:135], v[96:97], v[134:135]
	v_or_b32_e32 v216, 16, v160
	v_ashrrev_i32_e32 v217, 31, v216
	s_and_b64 vcc, exec, s[8:9]
	v_mov_b32_e32 v129, 0
	v_pk_fma_f32 v[98:99], v[132:133], v[126:127], v[170:171]
	v_pk_fma_f32 v[96:97], v[130:131], v[124:125], v[168:169]
	global_store_dwordx4 v[150:151], v[96:99], off sc1
	v_pk_fma_f32 v[102:103], v[132:133], v[118:119], v[178:179]
	s_nop 0
	v_pk_fma_f32 v[98:99], v[132:133], v[122:123], v[174:175]
	v_pk_fma_f32 v[96:97], v[130:131], v[120:121], v[172:173]
	v_pk_fma_f32 v[100:101], v[130:131], v[116:117], v[176:177]
	v_pk_fma_f32 v[106:107], v[132:133], v[114:115], v[182:183]
	v_pk_fma_f32 v[104:105], v[130:131], v[112:113], v[180:181]
	v_pk_fma_f32 v[110:111], v[132:133], v[110:111], v[186:187]
	v_pk_fma_f32 v[108:109], v[130:131], v[108:109], v[184:185]
	v_pk_fma_f32 v[114:115], v[132:133], v[208:209], v[190:191]
	v_pk_fma_f32 v[112:113], v[130:131], v[210:211], v[188:189]
	v_pk_fma_f32 v[118:119], v[132:133], v[212:213], v[194:195]
	v_pk_fma_f32 v[116:117], v[130:131], v[214:215], v[192:193]
	v_pk_fma_f32 v[122:123], v[132:133], v[136:137], v[198:199]
	v_pk_fma_f32 v[120:121], v[130:131], v[134:135], v[196:197]
	global_store_dwordx4 v[152:153], v[96:99], off sc1
	global_store_dwordx4 v[154:155], v[100:103], off sc1
	global_store_dwordx4 v[156:157], v[104:107], off sc1
	global_store_dwordx4 v[200:201], v[108:111], off sc1
	global_store_dwordx4 v[202:203], v[112:115], off sc1
	global_store_dwordx4 v[204:205], v[116:119], off sc1
	global_store_dwordx4 v[206:207], v[120:123], off sc1
	v_lshl_add_u64 v[96:97], v[216:217], 2, s[14:15]
	global_load_dwordx4 v[96:99], v[96:97], off
	v_mov_b32_e32 v130, 0
	v_mov_b32_e32 v131, 0
	s_cbranch_vccnz .LBB0_1538
	flat_load_dwordx4 v[128:131], v[158:159] offset:64
.LBB0_1538:
	v_lshl_add_u64 v[100:101], v[150:151], 0, s[20:21]
	global_load_dwordx4 v[108:111], v[150:151], off offset:64
	global_load_dwordx4 v[112:115], v[152:153], off offset:64
	global_load_dwordx4 v[116:119], v[154:155], off offset:64
	global_load_dwordx4 v[120:123], v[156:157], off offset:64
	global_load_dwordx4 v[124:127], v[100:101], off offset:64
	v_lshl_add_u64 v[102:103], v[150:151], 0, s[46:47]
	v_lshl_add_u64 v[104:105], v[150:151], 0, s[50:51]
	v_lshl_add_u64 v[106:107], v[150:151], 0, s[54:55]
	global_load_dwordx4 v[132:135], v[102:103], off offset:64
	global_load_dwordx4 v[168:171], v[104:105], off offset:64
	global_load_dwordx4 v[172:175], v[106:107], off offset:64
	s_waitcnt vmcnt(0) lgkmcnt(0)
	v_pk_add_f32 v[94:95], v[94:95], v[130:131]
	v_pk_add_f32 v[92:93], v[92:93], v[128:129]
	v_pk_add_f32 v[90:91], v[90:91], v[130:131]
	v_pk_add_f32 v[88:89], v[88:89], v[128:129]
	v_pk_add_f32 v[86:87], v[86:87], v[130:131]
	v_pk_add_f32 v[84:85], v[84:85], v[128:129]
	v_pk_add_f32 v[82:83], v[82:83], v[130:131]
	v_pk_add_f32 v[80:81], v[80:81], v[128:129]
	v_pk_add_f32 v[136:137], v[78:79], v[130:131]
	v_pk_add_f32 v[176:177], v[76:77], v[128:129]
	v_pk_add_f32 v[178:179], v[74:75], v[130:131]
	v_pk_add_f32 v[180:181], v[72:73], v[128:129]
	v_pk_add_f32 v[182:183], v[70:71], v[130:131]
	v_pk_add_f32 v[184:185], v[68:69], v[128:129]
	v_pk_add_f32 v[130:131], v[66:67], v[130:131]
	v_pk_add_f32 v[128:129], v[64:65], v[128:129]
	v_or_b32_e32 v186, 0x80, v160
	v_ashrrev_i32_e32 v187, 31, v186
	s_and_b64 vcc, exec, s[8:9]
	v_pk_fma_f32 v[66:67], v[98:99], v[94:95], v[110:111]
	v_pk_fma_f32 v[64:65], v[96:97], v[92:93], v[108:109]
	v_pk_fma_f32 v[70:71], v[98:99], v[90:91], v[114:115]
	v_pk_fma_f32 v[68:69], v[96:97], v[88:89], v[112:113]
	v_pk_fma_f32 v[74:75], v[98:99], v[86:87], v[118:119]
	v_pk_fma_f32 v[72:73], v[96:97], v[84:85], v[116:117]
	v_pk_fma_f32 v[78:79], v[98:99], v[82:83], v[122:123]
	v_pk_fma_f32 v[76:77], v[96:97], v[80:81], v[120:121]
	global_store_dwordx4 v[150:151], v[64:67], off offset:64 sc1
	global_store_dwordx4 v[152:153], v[68:71], off offset:64 sc1
	global_store_dwordx4 v[154:155], v[72:75], off offset:64 sc1
	global_store_dwordx4 v[156:157], v[76:79], off offset:64 sc1
	v_pk_fma_f32 v[66:67], v[98:99], v[136:137], v[126:127]
	v_pk_fma_f32 v[64:65], v[96:97], v[176:177], v[124:125]
	v_pk_fma_f32 v[70:71], v[98:99], v[178:179], v[134:135]
	v_pk_fma_f32 v[68:69], v[96:97], v[180:181], v[132:133]
	v_pk_fma_f32 v[74:75], v[98:99], v[182:183], v[170:171]
	v_pk_fma_f32 v[72:73], v[96:97], v[184:185], v[168:169]
	v_pk_fma_f32 v[78:79], v[98:99], v[130:131], v[174:175]
	v_pk_fma_f32 v[76:77], v[96:97], v[128:129], v[172:173]
	global_store_dwordx4 v[100:101], v[64:67], off offset:64 sc1
	global_store_dwordx4 v[102:103], v[68:71], off offset:64 sc1
	global_store_dwordx4 v[104:105], v[72:75], off offset:64 sc1
	global_store_dwordx4 v[106:107], v[76:79], off offset:64 sc1
	v_lshl_add_u64 v[64:65], v[186:187], 2, s[14:15]
	global_load_dwordx4 v[66:69], v[64:65], off
	v_mov_b32_e32 v64, 0
	v_mov_b32_e32 v70, 0
	v_mov_b32_e32 v71, 0
	v_mov_b32_e32 v72, 0
	v_mov_b32_e32 v73, 0
	s_cbranch_vccnz .LBB0_1540
	flat_load_dwordx4 v[70:73], v[158:159] offset:512
.LBB0_1540:
	global_load_dwordx4 v[74:77], v[150:151], off offset:512
	global_load_dwordx4 v[78:81], v[152:153], off offset:512
	global_load_dwordx4 v[82:85], v[154:155], off offset:512
	global_load_dwordx4 v[86:89], v[156:157], off offset:512
	global_load_dwordx4 v[90:93], v[100:101], off offset:512
	global_load_dwordx4 v[94:97], v[102:103], off offset:512
	global_load_dwordx4 v[108:111], v[104:105], off offset:512
	global_load_dwordx4 v[112:115], v[106:107], off offset:512
	s_waitcnt vmcnt(0) lgkmcnt(0)
	v_pk_add_f32 v[62:63], v[62:63], v[72:73]
	v_pk_add_f32 v[60:61], v[60:61], v[70:71]
	v_or_b32_e32 v126, 0x90, v160
	v_pk_add_f32 v[58:59], v[58:59], v[72:73]
	v_pk_add_f32 v[56:57], v[56:57], v[70:71]
	v_pk_add_f32 v[54:55], v[54:55], v[72:73]
	v_pk_add_f32 v[52:53], v[52:53], v[70:71]
	v_pk_add_f32 v[50:51], v[50:51], v[72:73]
	v_pk_add_f32 v[48:49], v[48:49], v[70:71]
	v_pk_add_f32 v[98:99], v[46:47], v[72:73]
	v_pk_add_f32 v[116:117], v[44:45], v[70:71]
	v_pk_add_f32 v[118:119], v[42:43], v[72:73]
	v_pk_add_f32 v[120:121], v[40:41], v[70:71]
	v_pk_add_f32 v[122:123], v[38:39], v[72:73]
	v_pk_add_f32 v[124:125], v[36:37], v[70:71]
	v_pk_add_f32 v[72:73], v[34:35], v[72:73]
	v_pk_add_f32 v[70:71], v[32:33], v[70:71]
	v_ashrrev_i32_e32 v127, 31, v126
	s_and_b64 vcc, exec, s[8:9]
	v_mov_b32_e32 v65, 0
	v_pk_fma_f32 v[34:35], v[68:69], v[62:63], v[76:77]
	v_pk_fma_f32 v[32:33], v[66:67], v[60:61], v[74:75]
	v_pk_fma_f32 v[38:39], v[68:69], v[58:59], v[80:81]
	v_pk_fma_f32 v[36:37], v[66:67], v[56:57], v[78:79]
	v_pk_fma_f32 v[42:43], v[68:69], v[54:55], v[84:85]
	v_pk_fma_f32 v[40:41], v[66:67], v[52:53], v[82:83]
	v_pk_fma_f32 v[46:47], v[68:69], v[50:51], v[88:89]
	v_pk_fma_f32 v[44:45], v[66:67], v[48:49], v[86:87]
	v_pk_fma_f32 v[50:51], v[68:69], v[98:99], v[92:93]
	v_pk_fma_f32 v[48:49], v[66:67], v[116:117], v[90:91]
	v_pk_fma_f32 v[54:55], v[68:69], v[118:119], v[96:97]
	v_pk_fma_f32 v[52:53], v[66:67], v[120:121], v[94:95]
	v_pk_fma_f32 v[58:59], v[68:69], v[122:123], v[110:111]
	v_pk_fma_f32 v[56:57], v[66:67], v[124:125], v[108:109]
	v_pk_fma_f32 v[62:63], v[68:69], v[72:73], v[114:115]
	v_pk_fma_f32 v[60:61], v[66:67], v[70:71], v[112:113]
	global_store_dwordx4 v[150:151], v[32:35], off offset:512 sc1
	global_store_dwordx4 v[152:153], v[36:39], off offset:512 sc1
	global_store_dwordx4 v[154:155], v[40:43], off offset:512 sc1
	global_store_dwordx4 v[156:157], v[44:47], off offset:512 sc1
	global_store_dwordx4 v[100:101], v[48:51], off offset:512 sc1
	global_store_dwordx4 v[102:103], v[52:55], off offset:512 sc1
	global_store_dwordx4 v[104:105], v[56:59], off offset:512 sc1
	global_store_dwordx4 v[106:107], v[60:63], off offset:512 sc1
	v_lshl_add_u64 v[32:33], v[126:127], 2, s[14:15]
	global_load_dwordx4 v[32:35], v[32:33], off
	v_mov_b32_e32 v66, 0
	v_mov_b32_e32 v67, 0
	s_cbranch_vccnz .LBB0_1525
	flat_load_dwordx4 v[64:67], v[158:159] offset:576
	s_branch .LBB0_1525

.LBB0_1749:
	ds_read_b128 v[128:131], v221
	ds_read_b128 v[132:135], v221 offset:1024
	ds_read_b128 v[136:139], v221 offset:2048
	ds_read_b128 v[140:143], v221 offset:3072
	s_add_u32 s44, s42, 0x100
	s_addc_u32 s45, s43, 0
	s_cmpk_eq_i32 s61, 0x54
	s_cselect_b32 s5, s9, s45
	s_cselect_b32 s4, s8, s44
	s_cselect_b32 s47, s11, s1
	s_cselect_b32 s46, s10, s0
	s_add_i32 m0, s25, 0xc000
	ds_read_b128 v[144:147], v222
	ds_read_b128 v[148:151], v222 offset:1024
	ds_read_b128 v[152:155], v222 offset:2048
	ds_read_b128 v[156:159], v222 offset:3072
	ds_read_b128 v[160:163], v222 offset:4096
	ds_read_b128 v[176:179], v222 offset:5120
	ds_read_b128 v[180:183], v222 offset:6144
	ds_read_b128 v[184:187], v222 offset:7168
	global_load_lds_dwordx4 v168, s[42:43]
	s_add_i32 m0, s25, 0xe000
	s_nop 0
	global_load_lds_dwordx4 v170, s[42:43]
	s_waitcnt lgkmcnt(8)
	s_barrier
	s_waitcnt lgkmcnt(0)
	s_waitcnt lgkmcnt(0)
	v_mfma_f32_16x16x32_bf16 v[124:127], v[128:131], v[144:147], v[124:127]
	v_mfma_f32_16x16x32_bf16 v[100:103], v[136:139], v[144:147], v[100:103]
	v_mfma_f32_16x16x32_bf16 v[120:123], v[128:131], v[152:155], v[120:123]
	v_mfma_f32_16x16x32_bf16 v[96:99], v[136:139], v[152:155], v[96:99]
	v_mfma_f32_16x16x32_bf16 v[116:119], v[128:131], v[160:163], v[116:119]
	v_mfma_f32_16x16x32_bf16 v[92:95], v[136:139], v[160:163], v[92:95]
	v_mfma_f32_16x16x32_bf16 v[112:115], v[128:131], v[180:183], v[112:115]
	v_mfma_f32_16x16x32_bf16 v[84:87], v[136:139], v[180:183], v[84:87]
	v_mfma_f32_16x16x32_bf16 v[124:127], v[132:135], v[148:151], v[124:127]
	v_mfma_f32_16x16x32_bf16 v[100:103], v[140:143], v[148:151], v[100:103]
	v_mfma_f32_16x16x32_bf16 v[120:123], v[132:135], v[156:159], v[120:123]
	v_mfma_f32_16x16x32_bf16 v[96:99], v[140:143], v[156:159], v[96:99]
	v_mfma_f32_16x16x32_bf16 v[116:119], v[132:135], v[176:179], v[116:119]
	v_mfma_f32_16x16x32_bf16 v[92:95], v[140:143], v[176:179], v[92:95]
	v_mfma_f32_16x16x32_bf16 v[112:115], v[132:135], v[184:187], v[112:115]
	v_mfma_f32_16x16x32_bf16 v[84:87], v[140:143], v[184:187], v[84:87]
	s_barrier
	s_add_i32 s42, s51, s24
	s_add_u32 s98, s46, s18
	s_addc_u32 s99, s47, s19
	s_mov_b32 m0, s42
	ds_read_b128 v[188:191], v223
	ds_read_b128 v[192:195], v223 offset:1024
	ds_read_b128 v[196:199], v223 offset:2048
	ds_read_b128 v[200:203], v223 offset:3072
	global_load_lds_dwordx4 v166, s[46:47]
	s_add_i32 m0, s42, 0x2000
	s_nop 0
	global_load_lds_dwordx4 v164, s[46:47]
	s_barrier
	s_waitcnt lgkmcnt(0)
	s_waitcnt lgkmcnt(0)
	v_mfma_f32_16x16x32_bf16 v[72:75], v[188:191], v[144:147], v[72:75]
	v_mfma_f32_16x16x32_bf16 v[44:47], v[196:199], v[144:147], v[44:47]
	v_mfma_f32_16x16x32_bf16 v[64:67], v[188:191], v[152:155], v[64:67]
	v_mfma_f32_16x16x32_bf16 v[40:43], v[196:199], v[152:155], v[40:43]
	v_mfma_f32_16x16x32_bf16 v[56:59], v[188:191], v[160:163], v[56:59]
	v_mfma_f32_16x16x32_bf16 v[36:39], v[196:199], v[160:163], v[36:39]
	v_mfma_f32_16x16x32_bf16 v[48:51], v[188:191], v[180:183], v[48:51]
	v_mfma_f32_16x16x32_bf16 v[28:31], v[196:199], v[180:183], v[28:31]
	v_mfma_f32_16x16x32_bf16 v[72:75], v[192:195], v[148:151], v[72:75]
	v_mfma_f32_16x16x32_bf16 v[44:47], v[200:203], v[148:151], v[44:47]
	v_mfma_f32_16x16x32_bf16 v[64:67], v[192:195], v[156:159], v[64:67]
	v_mfma_f32_16x16x32_bf16 v[40:43], v[200:203], v[156:159], v[40:43]
	v_mfma_f32_16x16x32_bf16 v[56:59], v[192:195], v[176:179], v[56:59]
	v_mfma_f32_16x16x32_bf16 v[36:39], v[200:203], v[176:179], v[36:39]
	v_mfma_f32_16x16x32_bf16 v[48:51], v[192:195], v[184:187], v[48:51]
	v_mfma_f32_16x16x32_bf16 v[28:31], v[200:203], v[184:187], v[28:31]
	s_mov_b32 m0, s25
	s_add_u32 s100, s4, s18
	s_addc_u32 s101, s5, s19
	s_barrier
	ds_read_b128 v[144:147], v222 offset:16384
	ds_read_b128 v[148:151], v222 offset:17408
	ds_read_b128 v[152:155], v222 offset:18432
	ds_read_b128 v[156:159], v222 offset:19456
	ds_read_b128 v[160:163], v222 offset:20480
	ds_read_b128 v[176:179], v222 offset:21504
	ds_read_b128 v[180:183], v222 offset:22528
	ds_read_b128 v[184:187], v222 offset:23552
	global_load_lds_dwordx4 v166, s[4:5]
	s_mov_b32 m0, s28
	s_nop 0
	global_load_lds_dwordx4 v164, s[4:5]
	s_barrier
	s_waitcnt lgkmcnt(0)
	s_waitcnt lgkmcnt(0)
	v_mfma_f32_16x16x32_bf16 v[108:111], v[128:131], v[144:147], v[108:111]
	v_mfma_f32_16x16x32_bf16 v[76:79], v[136:139], v[144:147], v[76:79]
	v_mfma_f32_16x16x32_bf16 v[104:107], v[128:131], v[152:155], v[104:107]
	v_mfma_f32_16x16x32_bf16 v[68:71], v[136:139], v[152:155], v[68:71]
	v_mfma_f32_16x16x32_bf16 v[88:91], v[128:131], v[160:163], v[88:91]
	v_mfma_f32_16x16x32_bf16 v[60:63], v[136:139], v[160:163], v[60:63]
	v_mfma_f32_16x16x32_bf16 v[80:83], v[128:131], v[180:183], v[80:83]
	v_mfma_f32_16x16x32_bf16 v[52:55], v[136:139], v[180:183], v[52:55]
	v_mfma_f32_16x16x32_bf16 v[108:111], v[132:135], v[148:151], v[108:111]
	v_mfma_f32_16x16x32_bf16 v[76:79], v[140:143], v[148:151], v[76:79]
	v_mfma_f32_16x16x32_bf16 v[104:107], v[132:135], v[156:159], v[104:107]
	v_mfma_f32_16x16x32_bf16 v[68:71], v[140:143], v[156:159], v[68:71]
	v_mfma_f32_16x16x32_bf16 v[88:91], v[132:135], v[176:179], v[88:91]
	v_mfma_f32_16x16x32_bf16 v[60:63], v[140:143], v[176:179], v[60:63]
	v_mfma_f32_16x16x32_bf16 v[80:83], v[132:135], v[184:187], v[80:83]
	v_mfma_f32_16x16x32_bf16 v[52:55], v[140:143], v[184:187], v[52:55]
	s_barrier
	s_add_u32 s42, s46, 0x160000
	s_addc_u32 s43, s47, 0
	s_add_i32 s62, s52, s24
	s_mov_b32 m0, s62
	s_nop 0
	global_load_lds_dwordx4 v166, s[42:43]
	s_add_i32 m0, s62, 0x2000
	s_nop 0
	global_load_lds_dwordx4 v164, s[42:43]
	s_waitcnt vmcnt(6)
	s_barrier
	v_mfma_f32_16x16x32_bf16 v[32:35], v[188:191], v[144:147], v[32:35]
	v_mfma_f32_16x16x32_bf16 v[12:15], v[196:199], v[144:147], v[12:15]
	v_mfma_f32_16x16x32_bf16 v[24:27], v[188:191], v[152:155], v[24:27]
	v_mfma_f32_16x16x32_bf16 v[8:11], v[196:199], v[152:155], v[8:11]
	v_mfma_f32_16x16x32_bf16 v[20:23], v[188:191], v[160:163], v[20:23]
	v_mfma_f32_16x16x32_bf16 v[4:7], v[196:199], v[160:163], v[4:7]
	v_mfma_f32_16x16x32_bf16 v[16:19], v[188:191], v[180:183], v[16:19]
	v_mfma_f32_16x16x32_bf16 v[0:3], v[196:199], v[180:183], v[0:3]
	v_mfma_f32_16x16x32_bf16 v[32:35], v[192:195], v[148:151], v[32:35]
	v_mfma_f32_16x16x32_bf16 v[12:15], v[200:203], v[148:151], v[12:15]
	v_mfma_f32_16x16x32_bf16 v[24:27], v[192:195], v[156:159], v[24:27]
	v_mfma_f32_16x16x32_bf16 v[8:11], v[200:203], v[156:159], v[8:11]
	v_mfma_f32_16x16x32_bf16 v[20:23], v[192:195], v[176:179], v[20:23]
	v_mfma_f32_16x16x32_bf16 v[4:7], v[200:203], v[176:179], v[4:7]
	v_mfma_f32_16x16x32_bf16 v[16:19], v[192:195], v[184:187], v[16:19]
	v_mfma_f32_16x16x32_bf16 v[0:3], v[200:203], v[184:187], v[0:3]
	s_add_i32 s42, 0, 0x18000
	v_add_u32_e32 v140, s42, v219
	s_barrier
	ds_read_b128 v[128:131], v140
	ds_read_b128 v[132:135], v140 offset:1024
	ds_read_b128 v[136:139], v140 offset:2048
	ds_read_b128 v[140:143], v140 offset:3072
	s_add_u32 s4, s4, 0x160000
	s_addc_u32 s5, s5, 0
	s_mov_b32 m0, s29
	ds_read_b128 v[144:147], v222 offset:32768
	ds_read_b128 v[148:151], v222 offset:33792
	ds_read_b128 v[152:155], v222 offset:34816
	ds_read_b128 v[156:159], v222 offset:35840
	ds_read_b128 v[160:163], v222 offset:36864
	ds_read_b128 v[176:179], v222 offset:37888
	ds_read_b128 v[180:183], v222 offset:38912
	ds_read_b128 v[184:187], v222 offset:39936
	global_load_lds_dwordx4 v166, s[4:5]
	s_mov_b32 m0, s33
	s_nop 0
	global_load_lds_dwordx4 v164, s[4:5]
	s_waitcnt lgkmcnt(8)
	s_barrier
	s_waitcnt lgkmcnt(0)
	s_waitcnt lgkmcnt(0)
	v_mfma_f32_16x16x32_bf16 v[124:127], v[128:131], v[144:147], v[124:127]
	v_mfma_f32_16x16x32_bf16 v[100:103], v[136:139], v[144:147], v[100:103]
	v_mfma_f32_16x16x32_bf16 v[120:123], v[128:131], v[152:155], v[120:123]
	v_mfma_f32_16x16x32_bf16 v[96:99], v[136:139], v[152:155], v[96:99]
	v_mfma_f32_16x16x32_bf16 v[116:119], v[128:131], v[160:163], v[116:119]
	v_mfma_f32_16x16x32_bf16 v[92:95], v[136:139], v[160:163], v[92:95]
	v_mfma_f32_16x16x32_bf16 v[112:115], v[128:131], v[180:183], v[112:115]
	v_mfma_f32_16x16x32_bf16 v[84:87], v[136:139], v[180:183], v[84:87]
	v_mfma_f32_16x16x32_bf16 v[124:127], v[132:135], v[148:151], v[124:127]
	v_mfma_f32_16x16x32_bf16 v[100:103], v[140:143], v[148:151], v[100:103]
	v_mfma_f32_16x16x32_bf16 v[120:123], v[132:135], v[156:159], v[120:123]
	v_mfma_f32_16x16x32_bf16 v[96:99], v[140:143], v[156:159], v[96:99]
	v_mfma_f32_16x16x32_bf16 v[116:119], v[132:135], v[176:179], v[116:119]
	v_mfma_f32_16x16x32_bf16 v[92:95], v[140:143], v[176:179], v[92:95]
	v_mfma_f32_16x16x32_bf16 v[112:115], v[132:135], v[184:187], v[112:115]
	v_mfma_f32_16x16x32_bf16 v[84:87], v[140:143], v[184:187], v[84:87]
	s_barrier
	s_add_i32 s43, 0, 0x1c000
	s_add_i32 s4, s42, s24
	v_add_u32_e32 v200, s43, v219
	s_mov_b32 m0, s4
	ds_read_b128 v[188:191], v200
	ds_read_b128 v[192:195], v200 offset:1024
	ds_read_b128 v[196:199], v200 offset:2048
	ds_read_b128 v[200:203], v200 offset:3072
	global_load_lds_dwordx4 v166, s[98:99]
	s_add_i32 m0, s4, 0x2000
	s_nop 0
	global_load_lds_dwordx4 v164, s[98:99]
	s_barrier
	s_waitcnt lgkmcnt(0)
	s_waitcnt lgkmcnt(0)
	v_mfma_f32_16x16x32_bf16 v[72:75], v[188:191], v[144:147], v[72:75]
	v_mfma_f32_16x16x32_bf16 v[44:47], v[196:199], v[144:147], v[44:47]
	v_mfma_f32_16x16x32_bf16 v[64:67], v[188:191], v[152:155], v[64:67]
	v_mfma_f32_16x16x32_bf16 v[40:43], v[196:199], v[152:155], v[40:43]
	v_mfma_f32_16x16x32_bf16 v[56:59], v[188:191], v[160:163], v[56:59]
	v_mfma_f32_16x16x32_bf16 v[36:39], v[196:199], v[160:163], v[36:39]
	v_mfma_f32_16x16x32_bf16 v[48:51], v[188:191], v[180:183], v[48:51]
	v_mfma_f32_16x16x32_bf16 v[28:31], v[196:199], v[180:183], v[28:31]
	v_mfma_f32_16x16x32_bf16 v[72:75], v[192:195], v[148:151], v[72:75]
	v_mfma_f32_16x16x32_bf16 v[44:47], v[200:203], v[148:151], v[44:47]
	v_mfma_f32_16x16x32_bf16 v[64:67], v[192:195], v[156:159], v[64:67]
	v_mfma_f32_16x16x32_bf16 v[40:43], v[200:203], v[156:159], v[40:43]
	v_mfma_f32_16x16x32_bf16 v[56:59], v[192:195], v[176:179], v[56:59]
	v_mfma_f32_16x16x32_bf16 v[36:39], v[200:203], v[176:179], v[36:39]
	v_mfma_f32_16x16x32_bf16 v[48:51], v[192:195], v[184:187], v[48:51]
	v_mfma_f32_16x16x32_bf16 v[28:31], v[200:203], v[184:187], v[28:31]
	s_mov_b32 m0, s41
	s_barrier
	ds_read_b128 v[144:147], v222 offset:49152
	ds_read_b128 v[148:151], v222 offset:50176
	ds_read_b128 v[152:155], v222 offset:51200
	ds_read_b128 v[156:159], v222 offset:52224
	ds_read_b128 v[160:163], v222 offset:53248
	ds_read_b128 v[176:179], v222 offset:54272
	ds_read_b128 v[180:183], v222 offset:55296
	ds_read_b128 v[184:187], v222 offset:56320
	global_load_lds_dwordx4 v166, s[100:101]
	s_mov_b32 m0, s50
	s_nop 0
	global_load_lds_dwordx4 v164, s[100:101]
	s_barrier
	s_waitcnt lgkmcnt(0)
	s_waitcnt lgkmcnt(0)
	v_mfma_f32_16x16x32_bf16 v[108:111], v[128:131], v[144:147], v[108:111]
	v_mfma_f32_16x16x32_bf16 v[76:79], v[136:139], v[144:147], v[76:79]
	v_mfma_f32_16x16x32_bf16 v[104:107], v[128:131], v[152:155], v[104:107]
	v_mfma_f32_16x16x32_bf16 v[68:71], v[136:139], v[152:155], v[68:71]
	v_mfma_f32_16x16x32_bf16 v[88:91], v[128:131], v[160:163], v[88:91]
	v_mfma_f32_16x16x32_bf16 v[60:63], v[136:139], v[160:163], v[60:63]
	v_mfma_f32_16x16x32_bf16 v[80:83], v[128:131], v[180:183], v[80:83]
	v_mfma_f32_16x16x32_bf16 v[52:55], v[136:139], v[180:183], v[52:55]
	v_mfma_f32_16x16x32_bf16 v[108:111], v[132:135], v[148:151], v[108:111]
	v_mfma_f32_16x16x32_bf16 v[76:79], v[140:143], v[148:151], v[76:79]
	v_mfma_f32_16x16x32_bf16 v[104:107], v[132:135], v[156:159], v[104:107]
	v_mfma_f32_16x16x32_bf16 v[68:71], v[140:143], v[156:159], v[68:71]
	v_mfma_f32_16x16x32_bf16 v[88:91], v[132:135], v[176:179], v[88:91]
	v_mfma_f32_16x16x32_bf16 v[60:63], v[140:143], v[176:179], v[60:63]
	v_mfma_f32_16x16x32_bf16 v[80:83], v[132:135], v[184:187], v[80:83]
	v_mfma_f32_16x16x32_bf16 v[52:55], v[140:143], v[184:187], v[52:55]
	s_barrier
	s_add_u32 s4, s46, 0x160080
	s_addc_u32 s5, s47, 0
	s_add_i32 s42, s43, s24
	s_mov_b32 m0, s42
	s_nop 0
	global_load_lds_dwordx4 v166, s[4:5]
	s_add_i32 m0, s42, 0x2000
	s_nop 0
	global_load_lds_dwordx4 v164, s[4:5]
	s_waitcnt vmcnt(6)
	s_barrier
	v_mfma_f32_16x16x32_bf16 v[32:35], v[188:191], v[144:147], v[32:35]
	v_mfma_f32_16x16x32_bf16 v[12:15], v[196:199], v[144:147], v[12:15]
	v_mfma_f32_16x16x32_bf16 v[24:27], v[188:191], v[152:155], v[24:27]
	v_mfma_f32_16x16x32_bf16 v[8:11], v[196:199], v[152:155], v[8:11]
	v_mfma_f32_16x16x32_bf16 v[20:23], v[188:191], v[160:163], v[20:23]
	v_mfma_f32_16x16x32_bf16 v[4:7], v[196:199], v[160:163], v[4:7]
	v_mfma_f32_16x16x32_bf16 v[16:19], v[188:191], v[180:183], v[16:19]
	v_mfma_f32_16x16x32_bf16 v[0:3], v[196:199], v[180:183], v[0:3]
	v_mfma_f32_16x16x32_bf16 v[32:35], v[192:195], v[148:151], v[32:35]
	v_mfma_f32_16x16x32_bf16 v[12:15], v[200:203], v[148:151], v[12:15]
	v_mfma_f32_16x16x32_bf16 v[24:27], v[192:195], v[156:159], v[24:27]
	v_mfma_f32_16x16x32_bf16 v[8:11], v[200:203], v[156:159], v[8:11]
	v_mfma_f32_16x16x32_bf16 v[20:23], v[192:195], v[176:179], v[20:23]
	v_mfma_f32_16x16x32_bf16 v[4:7], v[200:203], v[176:179], v[4:7]
	v_mfma_f32_16x16x32_bf16 v[16:19], v[192:195], v[184:187], v[16:19]
	v_mfma_f32_16x16x32_bf16 v[0:3], v[200:203], v[184:187], v[0:3]
	s_add_i32 s61, s61, 2
	s_add_u32 s0, s0, 0x100
	s_addc_u32 s1, s1, 0
	s_cmpk_gt_u32 s61, 0x55
	s_mov_b64 s[42:43], s[44:45]
	s_barrier
	s_cbranch_scc0 .LBB0_1749
	v_lshl_add_u32 v144, s59, 8, v218
	v_lshl_or_b32 v184, s60, 8, v220
	v_ashrrev_i32_e32 v145, 31, v144
	v_ashrrev_i32_e32 v185, 31, v184
	v_lshlrev_b64 v[132:133], 13, v[144:145]
	v_lshlrev_b64 v[146:147], 2, v[184:185]
	v_lshl_add_u64 v[132:133], s[12:13], 0, v[132:133]
	v_lshl_add_u64 v[176:177], v[132:133], 0, v[146:147]
	v_or_b32_e32 v136, 16, v144
	v_add_co_u32_e32 v186, vcc, s53, v176
	v_ashrrev_i32_e32 v137, 31, v136
	v_or_b32_e32 v140, 32, v144
	v_or_b32_e32 v144, 48, v144
	v_addc_co_u32_e32 v187, vcc, 0, v177, vcc
	v_lshlrev_b64 v[136:137], 13, v[136:137]
	v_ashrrev_i32_e32 v141, 31, v140
	v_ashrrev_i32_e32 v145, 31, v144
	v_add_co_u32_e32 v190, vcc, s54, v176
	v_lshl_add_u64 v[128:129], s[16:17], 0, v[146:147]
	v_lshl_add_u64 v[136:137], s[12:13], 0, v[136:137]
	v_lshlrev_b64 v[140:141], 13, v[140:141]
	v_lshlrev_b64 v[144:145], 13, v[144:145]
	v_addc_co_u32_e32 v191, vcc, 0, v177, vcc
	global_load_dwordx4 v[128:131], v[128:129], off
	v_lshl_add_u64 v[178:179], v[136:137], 0, v[146:147]
	global_load_dwordx4 v[132:135], v[176:177], off
	global_load_dwordx4 v[136:139], v[178:179], off
	v_lshl_add_u64 v[140:141], s[12:13], 0, v[140:141]
	v_lshl_add_u64 v[144:145], s[12:13], 0, v[144:145]
	v_add_co_u32_e32 v192, vcc, s55, v176
	v_lshl_add_u64 v[180:181], v[140:141], 0, v[146:147]
	v_lshl_add_u64 v[182:183], v[144:145], 0, v[146:147]
	v_addc_co_u32_e32 v193, vcc, 0, v177, vcc
	global_load_dwordx4 v[140:143], v[180:181], off
	global_load_dwordx4 v[144:147], v[182:183], off
	global_load_dwordx4 v[148:151], v[186:187], off
	global_load_dwordx4 v[160:163], v[190:191], off
	global_load_dwordx4 v[156:159], v[192:193], off
	v_add_co_u32_e32 v188, vcc, s56, v176
	v_pk_add_f32 v[212:213], v[126:127], 0 op_sel_hi:[1,0]
	s_nop 0
	v_addc_co_u32_e32 v189, vcc, 0, v177, vcc
	global_load_dwordx4 v[152:155], v[188:189], off
	v_pk_add_f32 v[214:215], v[124:125], 0 op_sel_hi:[1,0]
	v_pk_add_f32 v[126:127], v[122:123], 0 op_sel_hi:[1,0]
	v_pk_add_f32 v[194:195], v[120:121], 0 op_sel_hi:[1,0]
	v_pk_add_f32 v[196:197], v[118:119], 0 op_sel_hi:[1,0]
	v_pk_add_f32 v[198:199], v[116:117], 0 op_sel_hi:[1,0]
	v_pk_add_f32 v[200:201], v[114:115], 0 op_sel_hi:[1,0]
	v_pk_add_f32 v[202:203], v[112:113], 0 op_sel_hi:[1,0]
	v_pk_add_f32 v[204:205], v[110:111], 0 op_sel_hi:[1,0]
	v_pk_add_f32 v[206:207], v[108:109], 0 op_sel_hi:[1,0]
	v_pk_add_f32 v[208:209], v[106:107], 0 op_sel_hi:[1,0]
	v_pk_add_f32 v[210:211], v[104:105], 0 op_sel_hi:[1,0]
	v_lshl_add_u64 v[120:121], v[176:177], 0, s[20:21]
	v_lshl_add_u64 v[122:123], v[176:177], 0, s[36:37]
	global_load_dwordx4 v[104:107], v[176:177], off offset:64
	global_load_dwordx4 v[108:111], v[178:179], off offset:64
	global_load_dwordx4 v[112:115], v[180:181], off offset:64
	global_load_dwordx4 v[116:119], v[182:183], off offset:64
	global_load_dwordx4 v[224:227], v[120:121], off offset:576
	global_load_dwordx4 v[228:231], v[122:123], off offset:576
	v_lshl_add_u64 v[124:125], v[176:177], 0, s[38:39]
	v_pk_add_f32 v[102:103], v[102:103], 0 op_sel_hi:[1,0]
	v_pk_add_f32 v[100:101], v[100:101], 0 op_sel_hi:[1,0]
	v_pk_add_f32 v[98:99], v[98:99], 0 op_sel_hi:[1,0]
	v_pk_add_f32 v[96:97], v[96:97], 0 op_sel_hi:[1,0]
	v_pk_add_f32 v[74:75], v[74:75], 0 op_sel_hi:[1,0]
	v_pk_add_f32 v[72:73], v[72:73], 0 op_sel_hi:[1,0]
	v_pk_add_f32 v[66:67], v[66:67], 0 op_sel_hi:[1,0]
	v_pk_add_f32 v[64:65], v[64:65], 0 op_sel_hi:[1,0]
	v_pk_add_f32 v[58:59], v[58:59], 0 op_sel_hi:[1,0]
	v_pk_add_f32 v[56:57], v[56:57], 0 op_sel_hi:[1,0]
	v_pk_add_f32 v[46:47], v[46:47], 0 op_sel_hi:[1,0]
	v_pk_add_f32 v[44:45], v[44:45], 0 op_sel_hi:[1,0]
	v_pk_add_f32 v[42:43], v[42:43], 0 op_sel_hi:[1,0]
	v_pk_add_f32 v[40:41], v[40:41], 0 op_sel_hi:[1,0]
	v_pk_add_f32 v[38:39], v[38:39], 0 op_sel_hi:[1,0]
	v_pk_add_f32 v[36:37], v[36:37], 0 op_sel_hi:[1,0]
	v_pk_add_f32 v[30:31], v[30:31], 0 op_sel_hi:[1,0]
	v_pk_add_f32 v[28:29], v[28:29], 0 op_sel_hi:[1,0]
	s_and_b64 vcc, exec, s[6:7]
	s_mov_b32 s60, s57
	s_mov_b32 s59, s58
	s_mov_b64 s[44:45], s[10:11]
	s_mov_b64 s[42:43], s[8:9]
	s_waitcnt vmcnt(0)
	v_pk_fma_f32 v[134:135], v[212:213], v[130:131], v[134:135]
	v_pk_fma_f32 v[132:133], v[214:215], v[128:129], v[132:133]
	global_store_dwordx4 v[176:177], v[132:135], off sc1
	s_nop 1
	v_pk_fma_f32 v[134:135], v[126:127], v[130:131], v[138:139]
	v_pk_fma_f32 v[132:133], v[194:195], v[128:129], v[136:137]
	v_pk_add_f32 v[126:127], v[90:91], 0 op_sel_hi:[1,0]
	v_pk_fma_f32 v[138:139], v[196:197], v[130:131], v[142:143]
	v_pk_fma_f32 v[136:137], v[198:199], v[128:129], v[140:141]
	v_pk_fma_f32 v[142:143], v[200:201], v[130:131], v[146:147]
	v_pk_fma_f32 v[140:141], v[202:203], v[128:129], v[144:145]
	v_pk_fma_f32 v[146:147], v[204:205], v[130:131], v[150:151]
	v_pk_fma_f32 v[144:145], v[206:207], v[128:129], v[148:149]
	v_pk_fma_f32 v[150:151], v[208:209], v[130:131], v[162:163]
	v_pk_fma_f32 v[148:149], v[210:211], v[128:129], v[160:161]
	global_store_dwordx4 v[178:179], v[132:135], off sc1
	global_store_dwordx4 v[180:181], v[136:139], off sc1
	global_store_dwordx4 v[182:183], v[140:143], off sc1
	global_store_dwordx4 v[186:187], v[144:147], off sc1
	global_store_dwordx4 v[190:191], v[148:151], off sc1
	v_pk_add_f32 v[132:133], v[88:89], 0 op_sel_hi:[1,0]
	v_pk_fma_f32 v[134:135], v[126:127], v[130:131], v[158:159]
	v_pk_fma_f32 v[132:133], v[132:133], v[128:129], v[156:157]
	v_pk_add_f32 v[126:127], v[82:83], 0 op_sel_hi:[1,0]
	global_store_dwordx4 v[192:193], v[132:135], off sc1
	v_pk_fma_f32 v[130:131], v[126:127], v[130:131], v[154:155]
	v_or_b32_e32 v126, 16, v184
	v_pk_add_f32 v[132:133], v[80:81], 0 op_sel_hi:[1,0]
	v_ashrrev_i32_e32 v127, 31, v126
	v_pk_fma_f32 v[128:129], v[132:133], v[128:129], v[152:153]
	v_lshl_add_u64 v[146:147], v[176:177], 0, s[14:15]
	global_store_dwordx4 v[188:189], v[128:131], off sc1
	v_lshl_add_u64 v[126:127], v[126:127], 2, s[16:17]
	global_load_dwordx4 v[88:91], v[124:125], off offset:576
	global_load_dwordx4 v[80:83], v[146:147], off offset:576
	s_nop 0
	global_load_dwordx4 v[126:129], v[126:127], off
	s_nop 0
	global_load_dwordx4 v[130:133], v[120:121], off offset:64
	global_load_dwordx4 v[134:137], v[122:123], off offset:64
	global_load_dwordx4 v[138:141], v[124:125], off offset:64
	global_load_dwordx4 v[142:145], v[146:147], off offset:64
	v_pk_add_f32 v[192:193], v[52:53], 0 op_sel_hi:[1,0]
	v_or_b32_e32 v52, 0x80, v184
	v_pk_add_f32 v[148:149], v[94:95], 0 op_sel_hi:[1,0]
	v_pk_add_f32 v[150:151], v[92:93], 0 op_sel_hi:[1,0]
	v_pk_add_f32 v[152:153], v[86:87], 0 op_sel_hi:[1,0]
	v_pk_add_f32 v[154:155], v[84:85], 0 op_sel_hi:[1,0]
	v_pk_add_f32 v[156:157], v[78:79], 0 op_sel_hi:[1,0]
	v_pk_add_f32 v[158:159], v[76:77], 0 op_sel_hi:[1,0]
	v_pk_add_f32 v[160:161], v[70:71], 0 op_sel_hi:[1,0]
	v_pk_add_f32 v[162:163], v[68:69], 0 op_sel_hi:[1,0]
	v_pk_add_f32 v[186:187], v[62:63], 0 op_sel_hi:[1,0]
	v_pk_add_f32 v[188:189], v[60:61], 0 op_sel_hi:[1,0]
	v_pk_add_f32 v[190:191], v[54:55], 0 op_sel_hi:[1,0]
	v_ashrrev_i32_e32 v53, 31, v52
	v_lshl_add_u64 v[194:195], v[52:53], 2, s[16:17]
	global_load_dwordx4 v[52:55], v[176:177], off offset:512
	global_load_dwordx4 v[60:63], v[120:121], off offset:512
	global_load_dwordx4 v[68:71], v[122:123], off offset:512
	global_load_dwordx4 v[76:79], v[124:125], off offset:512
	global_load_dwordx4 v[84:87], v[146:147], off offset:512
	s_waitcnt vmcnt(0)
	v_pk_fma_f32 v[94:95], v[102:103], v[128:129], v[106:107]
	v_pk_fma_f32 v[92:93], v[100:101], v[126:127], v[104:105]
	v_pk_fma_f32 v[98:99], v[98:99], v[128:129], v[110:111]
	v_pk_fma_f32 v[96:97], v[96:97], v[126:127], v[108:109]
	v_pk_fma_f32 v[102:103], v[148:149], v[128:129], v[114:115]
	v_pk_fma_f32 v[100:101], v[150:151], v[126:127], v[112:113]
	v_pk_fma_f32 v[106:107], v[152:153], v[128:129], v[118:119]
	v_pk_fma_f32 v[104:105], v[154:155], v[126:127], v[116:117]
	v_pk_fma_f32 v[110:111], v[156:157], v[128:129], v[132:133]
	v_pk_fma_f32 v[108:109], v[158:159], v[126:127], v[130:131]
	v_pk_fma_f32 v[114:115], v[160:161], v[128:129], v[136:137]
	v_pk_fma_f32 v[112:113], v[162:163], v[126:127], v[134:135]
	v_pk_fma_f32 v[118:119], v[186:187], v[128:129], v[140:141]
	v_pk_fma_f32 v[116:117], v[188:189], v[126:127], v[138:139]
	v_pk_fma_f32 v[128:129], v[190:191], v[128:129], v[144:145]
	v_pk_fma_f32 v[126:127], v[192:193], v[126:127], v[142:143]
	global_store_dwordx4 v[176:177], v[92:95], off offset:64 sc1
	global_store_dwordx4 v[178:179], v[96:99], off offset:64 sc1
	global_store_dwordx4 v[180:181], v[100:103], off offset:64 sc1
	global_store_dwordx4 v[182:183], v[104:107], off offset:64 sc1
	global_store_dwordx4 v[120:121], v[108:111], off offset:64 sc1
	global_store_dwordx4 v[122:123], v[112:115], off offset:64 sc1
	global_store_dwordx4 v[124:125], v[116:119], off offset:64 sc1
	global_store_dwordx4 v[146:147], v[126:129], off offset:64 sc1
	global_load_dwordx4 v[92:95], v[194:195], off
	global_load_dwordx4 v[96:99], v[178:179], off offset:512
	global_load_dwordx4 v[100:103], v[180:181], off offset:512
	global_load_dwordx4 v[104:107], v[182:183], off offset:512
	v_pk_add_f32 v[132:133], v[16:17], 0 op_sel_hi:[1,0]
	v_or_b32_e32 v16, 0x90, v184
	v_pk_add_f32 v[108:109], v[50:51], 0 op_sel_hi:[1,0]
	v_pk_add_f32 v[110:111], v[48:49], 0 op_sel_hi:[1,0]
	v_pk_add_f32 v[112:113], v[34:35], 0 op_sel_hi:[1,0]
	v_pk_add_f32 v[114:115], v[32:33], 0 op_sel_hi:[1,0]
	v_pk_add_f32 v[116:117], v[26:27], 0 op_sel_hi:[1,0]
	v_pk_add_f32 v[118:119], v[24:25], 0 op_sel_hi:[1,0]
	v_pk_add_f32 v[126:127], v[22:23], 0 op_sel_hi:[1,0]
	v_pk_add_f32 v[128:129], v[20:21], 0 op_sel_hi:[1,0]
	v_pk_add_f32 v[130:131], v[18:19], 0 op_sel_hi:[1,0]
	v_ashrrev_i32_e32 v17, 31, v16
	v_lshl_add_u64 v[134:135], v[16:17], 2, s[16:17]
	global_load_dwordx4 v[16:19], v[176:177], off offset:576
	global_load_dwordx4 v[20:23], v[178:179], off offset:576
	global_load_dwordx4 v[24:27], v[180:181], off offset:576
	global_load_dwordx4 v[32:35], v[182:183], off offset:576
	s_waitcnt vmcnt(0)
	v_pk_fma_f32 v[50:51], v[74:75], v[94:95], v[54:55]
	v_pk_fma_f32 v[48:49], v[72:73], v[92:93], v[52:53]
	v_pk_fma_f32 v[54:55], v[66:67], v[94:95], v[98:99]
	v_pk_fma_f32 v[52:53], v[64:65], v[92:93], v[96:97]
	v_pk_fma_f32 v[58:59], v[58:59], v[94:95], v[102:103]
	v_pk_fma_f32 v[56:57], v[56:57], v[92:93], v[100:101]
	v_pk_fma_f32 v[66:67], v[108:109], v[94:95], v[106:107]
	v_pk_fma_f32 v[64:65], v[110:111], v[92:93], v[104:105]
	v_pk_fma_f32 v[62:63], v[112:113], v[94:95], v[62:63]
	v_pk_fma_f32 v[60:61], v[114:115], v[92:93], v[60:61]
	v_pk_fma_f32 v[70:71], v[116:117], v[94:95], v[70:71]
	v_pk_fma_f32 v[68:69], v[118:119], v[92:93], v[68:69]
	v_pk_fma_f32 v[74:75], v[126:127], v[94:95], v[78:79]
	v_pk_fma_f32 v[72:73], v[128:129], v[92:93], v[76:77]
	v_pk_fma_f32 v[78:79], v[130:131], v[94:95], v[86:87]
	v_pk_fma_f32 v[76:77], v[132:133], v[92:93], v[84:85]
	global_store_dwordx4 v[176:177], v[48:51], off offset:512 sc1
	global_store_dwordx4 v[178:179], v[52:55], off offset:512 sc1
	global_store_dwordx4 v[180:181], v[56:59], off offset:512 sc1
	global_store_dwordx4 v[182:183], v[64:67], off offset:512 sc1
	global_store_dwordx4 v[120:121], v[60:63], off offset:512 sc1
	global_store_dwordx4 v[122:123], v[68:71], off offset:512 sc1
	global_store_dwordx4 v[124:125], v[72:75], off offset:512 sc1
	global_store_dwordx4 v[146:147], v[76:79], off offset:512 sc1
	global_load_dwordx4 v[48:51], v[134:135], off
	v_pk_add_f32 v[52:53], v[14:15], 0 op_sel_hi:[1,0]
	v_pk_add_f32 v[54:55], v[12:13], 0 op_sel_hi:[1,0]
	v_pk_add_f32 v[56:57], v[10:11], 0 op_sel_hi:[1,0]
	v_pk_add_f32 v[58:59], v[8:9], 0 op_sel_hi:[1,0]
	v_pk_add_f32 v[60:61], v[6:7], 0 op_sel_hi:[1,0]
	v_pk_add_f32 v[62:63], v[4:5], 0 op_sel_hi:[1,0]
	v_pk_add_f32 v[64:65], v[2:3], 0 op_sel_hi:[1,0]
	v_pk_add_f32 v[66:67], v[0:1], 0 op_sel_hi:[1,0]
	s_waitcnt vmcnt(0)
	v_pk_fma_f32 v[2:3], v[46:47], v[50:51], v[18:19]
	v_pk_fma_f32 v[0:1], v[44:45], v[48:49], v[16:17]
	v_pk_fma_f32 v[6:7], v[42:43], v[50:51], v[22:23]
	v_pk_fma_f32 v[4:5], v[40:41], v[48:49], v[20:21]
	v_pk_fma_f32 v[10:11], v[38:39], v[50:51], v[26:27]
	v_pk_fma_f32 v[8:9], v[36:37], v[48:49], v[24:25]
	v_pk_fma_f32 v[14:15], v[30:31], v[50:51], v[34:35]
	v_pk_fma_f32 v[12:13], v[28:29], v[48:49], v[32:33]
	v_pk_fma_f32 v[18:19], v[52:53], v[50:51], v[226:227]
	v_pk_fma_f32 v[16:17], v[54:55], v[48:49], v[224:225]
	v_pk_fma_f32 v[22:23], v[56:57], v[50:51], v[230:231]
	v_pk_fma_f32 v[20:21], v[58:59], v[48:49], v[228:229]
	v_pk_fma_f32 v[26:27], v[60:61], v[50:51], v[90:91]
	v_pk_fma_f32 v[24:25], v[62:63], v[48:49], v[88:89]
	v_pk_fma_f32 v[30:31], v[64:65], v[50:51], v[82:83]
	v_pk_fma_f32 v[28:29], v[66:67], v[48:49], v[80:81]
	global_store_dwordx4 v[176:177], v[0:3], off offset:576 sc1
	global_store_dwordx4 v[178:179], v[4:7], off offset:576 sc1
	global_store_dwordx4 v[180:181], v[8:11], off offset:576 sc1
	global_store_dwordx4 v[182:183], v[12:15], off offset:576 sc1
	global_store_dwordx4 v[120:121], v[16:19], off offset:576 sc1
	global_store_dwordx4 v[122:123], v[20:23], off offset:576 sc1
	global_store_dwordx4 v[124:125], v[24:27], off offset:576 sc1
	global_store_dwordx4 v[146:147], v[28:31], off offset:576 sc1
	s_cbranch_vccz .LBB0_1738
	s_waitcnt vmcnt(0)
	s_cmpk_gt_u32 s23, 0xff
	s_cbranch_scc1 .LBB0_1753
	s_barrier
